# attention waits: Q-fragment vmcnt waits hoisted out of B/C tile loops; A odd-tile next loads issued after the register shuffle
# speedup vs baseline: 1.0088x; 1.0088x over previous
; #define LAS __attribute__((address_space(3)))
; #define SCHED_FENCE() __builtin_amdgcn_sched_barrier(0)
; template <int NC, bool DIAG>
; __device__ __forceinline__ void attn_tile(f32x16 (&O)[4], float& l, const bf16x8* Q, const LAS char* Kb, const LAS char* Vb, int r32, int hi, int lane, float qd, int k0, int qw, float nslope, float negM0) {
;     ...
;     const int k1 = k0 + 32;
;     if (NC == 2) {
;         const float ns0 = (k0 < qw) ? nslope : ((k0 > qw) ? -nslope : 0.f), ns1 = (k1 < qw) ? nslope : ((k1 > qw) ? -nslope : 0.f);
;         const float b0 = fmaf(ns0, qd - (float)k0, negM0), b1 = fmaf(ns1, qd - (float)k1, negM0);
; #pragma unroll
;         for (int r = 0; r < 16; ++r) { S0[r] = fmaf(-ns0, (float)((r & 3) + 8 * (r >> 2)), b0); S1[r] = fmaf(-ns1, (float)((r & 3) + 8 * (r >> 2)), b1); }
;     } else {
; #pragma unroll
;         for (int r = 0; r < 16; ++r) { S0[r] = negM0; S1[r] = negM0; }
;     }
;     VFrag vf0, vf1;
;     if (NC == 2) {
;         bf16x8 kf0[NQ], kf1[NQ];
;         kload32<NQ>(kf0, Kb, r32, hi);
;         SCHED_FENCE();
;         qkmm32<NQ>(S0, kf0, Q);
;         kload32<NQ>(kf1, Kb + 32 * KP, r32, hi);
;         vload16<0>(vf0, Vb, lane);
;         SCHED_FENCE();
;         qkmm32<NQ>(S1, kf1, Q);
;         if (DIAG) { const float nd = (k0 == qw) ? nslope : 0.f;
; #pragma unroll
;             for (int r = 0; r < 16; ++r) S0[r] = fmaf(nd, fabsf(qd - (float)k0 - (float)((r & 3) + 8 * (r >> 2))), S0[r]); }
;         soft32<0>(S0, P0, l, 0.f, 0.f);
;         vload16<1>(vf0, Vb, lane);
; template <int NC>
; __device__ __forceinline__ void attn_shared_unit(LAS char* lds, bf16* qbase, const bf16* Kg, const bf16* Vg, int kvp, int nt, int qpos, int qw, float nslope, float negM0, float lam, const float* subln, int wave_id) {
;     ...
;             if (t + 3 < t_hi) LOADB(t + 3);
;             int k0v = (t + 1) * 64; asm volatile("" : "+s"(k0v));
;             const LAS char* Kb = lds + BUFB + cm * 128; const LAS char* Vb = lds + BUFB + 64 * KP;
;             if (t + 1 == td) attn_tile<NC, true>(O, l, Q, Kb, Vb, r32, hi, lane, qd, k0v, qw, nslope, negM0);
;             else attn_tile<NC, false>(O, l, Q, Kb, Vb, r32, hi, lane, qd, k0v, qw, nslope, negM0);
.LBB0_281:
	s_mov_b32 s26, s89
	s_add_i32 s78, s26, 32
	s_cmp_lt_i32 s26, s87
	s_cselect_b64 vcc, -1, 0
	s_cmp_gt_i32 s26, s87
	s_cselect_b64 s[4:5], -1, 0
	v_cndmask_b32_e64 v0, 0, -v225, s[4:5]
	s_cmp_lt_i32 s78, s87
	v_cndmask_b32_e32 v218, v0, v225, vcc
	v_cvt_f32_i32_e32 v0, s26
	v_cvt_f32_i32_e32 v2, s78
	s_cselect_b64 s[4:5], -1, 0
	s_cmp_gt_i32 s78, s87
	s_cselect_b64 s[92:93], -1, 0
	v_cndmask_b32_e64 v1, 0, -v225, s[92:93]
	v_cndmask_b32_e64 v220, v1, v225, s[4:5]
	v_sub_f32_e32 v234, v219, v0
	v_sub_f32_e32 v233, v219, v2
	v_fma_f32 v142, v218, v234, v254
	v_fma_f32 v224, v220, v233, v254
	s_cmp_lg_u32 s91, 2
	v_fmamk_f32 v144, v218, 0x80000000, v142
	v_fmamk_f32 v128, v220, 0x80000000, v224
	s_mov_b64 s[4:5], -1
	v_sub_f32_e32 v145, v142, v218
	v_sub_f32_e32 v129, v224, v220
	s_cbranch_scc0 .LBB0_284
	ds_read_b128 v[16:19], v227 offset:37888
	ds_read_b128 v[20:23], v227 offset:37920
	ds_read_b128 v[24:27], v227 offset:37952
	ds_read_b128 v[28:31], v227 offset:37984
	v_pk_fma_f32 v[146:147], v[218:219], s[22:23], v[142:143] op_sel_hi:[0,1,0] neg_lo:[1,0,0] neg_hi:[1,0,0]
	v_pk_fma_f32 v[148:149], v[218:219], s[44:45], v[142:143] op_sel_hi:[0,1,0] neg_lo:[1,0,0] neg_hi:[1,0,0]
	v_pk_fma_f32 v[150:151], v[218:219], s[46:47], v[142:143] op_sel_hi:[0,1,0] neg_lo:[1,0,0] neg_hi:[1,0,0]
	v_pk_fma_f32 v[152:153], v[218:219], s[48:49], v[142:143] op_sel_hi:[0,1,0] neg_lo:[1,0,0] neg_hi:[1,0,0]
	v_pk_fma_f32 v[154:155], v[218:219], s[50:51], v[142:143] op_sel_hi:[0,1,0] neg_lo:[1,0,0] neg_hi:[1,0,0]
	v_pk_fma_f32 v[156:157], v[218:219], s[52:53], v[142:143] op_sel_hi:[0,1,0] neg_lo:[1,0,0] neg_hi:[1,0,0]
	v_pk_fma_f32 v[158:159], v[218:219], s[54:55], v[142:143] op_sel_hi:[0,1,0] neg_lo:[1,0,0] neg_hi:[1,0,0]
	v_pk_fma_f32 v[142:143], v[220:221], s[54:55], v[224:225] op_sel_hi:[0,1,0] neg_lo:[1,0,0] neg_hi:[1,0,0]
	v_pk_fma_f32 v[130:131], v[220:221], s[22:23], v[224:225] op_sel_hi:[0,1,0] neg_lo:[1,0,0] neg_hi:[1,0,0]
	v_pk_fma_f32 v[132:133], v[220:221], s[44:45], v[224:225] op_sel_hi:[0,1,0] neg_lo:[1,0,0] neg_hi:[1,0,0]
	v_pk_fma_f32 v[134:135], v[220:221], s[46:47], v[224:225] op_sel_hi:[0,1,0] neg_lo:[1,0,0] neg_hi:[1,0,0]
	v_pk_fma_f32 v[136:137], v[220:221], s[48:49], v[224:225] op_sel_hi:[0,1,0] neg_lo:[1,0,0] neg_hi:[1,0,0]
	v_pk_fma_f32 v[138:139], v[220:221], s[50:51], v[224:225] op_sel_hi:[0,1,0] neg_lo:[1,0,0] neg_hi:[1,0,0]
	v_pk_fma_f32 v[140:141], v[220:221], s[52:53], v[224:225] op_sel_hi:[0,1,0] neg_lo:[1,0,0] neg_hi:[1,0,0]
	v_mov_b64_e32 v[0:1], v[144:145]
	v_mov_b64_e32 v[2:3], v[146:147]
	v_mov_b64_e32 v[4:5], v[148:149]
	v_mov_b64_e32 v[6:7], v[150:151]
	v_mov_b64_e32 v[8:9], v[152:153]
	v_mov_b64_e32 v[10:11], v[154:155]
	v_mov_b64_e32 v[12:13], v[156:157]
	v_mov_b64_e32 v[14:15], v[158:159]
	s_waitcnt lgkmcnt(3)
	s_nop 0
	v_mfma_f32_32x32x16_bf16 v[0:15], v[16:19], v[162:165], v[0:15]
	s_waitcnt lgkmcnt(2)
	v_mfma_f32_32x32x16_bf16 v[0:15], v[20:23], v[166:169], v[0:15]
	ds_read_b128 v[16:19], v227 offset:46592
	ds_read_b128 v[20:23], v227 offset:46624
	ds_read_b128 v[32:35], v227 offset:46656
	ds_read_b128 v[36:39], v227 offset:46688
	s_waitcnt lgkmcnt(5)
	v_mfma_f32_32x32x16_bf16 v[0:15], v[24:27], v[170:173], v[0:15]
	ds_read_b64_tr_b16 v[24:25], v226 offset:55296
	ds_read_b64_tr_b16 v[236:237], v226 offset:55360
	ds_read_b64_tr_b16 v[240:241], v226 offset:55424
	ds_read_b64_tr_b16 v[244:245], v226 offset:55488
	ds_read_b64_tr_b16 v[26:27], v226 offset:57856
	ds_read_b64_tr_b16 v[238:239], v226 offset:57920
	ds_read_b64_tr_b16 v[242:243], v226 offset:57984
	ds_read_b64_tr_b16 v[246:247], v226 offset:58048
	s_waitcnt lgkmcnt(12)
	v_mfma_f32_32x32x16_bf16 v[0:15], v[28:31], v[174:177], v[0:15]
	v_mov_b64_e32 v[160:161], v[142:143]
	v_mov_b64_e32 v[158:159], v[140:141]
	v_mov_b64_e32 v[156:157], v[138:139]
	v_mov_b64_e32 v[154:155], v[136:137]
	v_mov_b64_e32 v[152:153], v[134:135]
	v_mov_b64_e32 v[150:151], v[132:133]
	v_mov_b64_e32 v[148:149], v[130:131]
	v_mov_b64_e32 v[146:147], v[128:129]
	s_nop 3
	v_exp_f32_e32 v0, v0
	v_exp_f32_e32 v1, v1
	s_waitcnt lgkmcnt(11)
	v_mfma_f32_32x32x16_bf16 v[146:161], v[16:19], v[162:165], v[146:161]
	v_exp_f32_e32 v2, v2
	v_exp_f32_e32 v3, v3
	v_add_f32_e32 v28, v232, v0
	v_exp_f32_e32 v4, v4
	v_add_f32_e32 v16, v1, v28
	v_exp_f32_e32 v5, v5
	v_add_f32_e32 v16, v2, v16
	s_waitcnt lgkmcnt(10)
	v_mfma_f32_32x32x16_bf16 v[146:161], v[20:23], v[166:169], v[146:161]
	v_exp_f32_e32 v6, v6
	v_add_f32_e32 v16, v3, v16
	v_exp_f32_e32 v7, v7
	v_mov_b64_e32 v[230:231], v[208:209]
	s_waitcnt vmcnt(1)
	v_mov_b64_e32 v[208:209], v[200:201]
	v_add_f32_e32 v16, v4, v16
	v_exp_f32_e32 v8, v8
	s_waitcnt lgkmcnt(9)
	v_mfma_f32_32x32x16_bf16 v[146:161], v[32:35], v[170:173], v[146:161]
	v_mov_b64_e32 v[206:207], v[198:199]
	v_mov_b64_e32 v[200:201], v[188:189]
	v_add_f32_e32 v16, v5, v16
	v_exp_f32_e32 v9, v9
	v_mov_b64_e32 v[198:199], v[186:187]
	v_mov_b64_e32 v[188:189], v[184:185]
	v_add_f32_e32 v16, v6, v16
	v_exp_f32_e32 v10, v10
	v_mov_b64_e32 v[186:187], v[182:183]
	v_mov_b64_e32 v[182:183], v[194:195]
	v_add_f32_e32 v16, v7, v16
	v_exp_f32_e32 v11, v11
	v_mov_b64_e32 v[184:185], v[196:197]
	v_mov_b64_e32 v[196:197], v[180:181]
	v_add_f32_e32 v16, v8, v16
	v_exp_f32_e32 v12, v12
	ds_read_b64_tr_b16 v[134:135], v226 offset:60416
	ds_read_b64_tr_b16 v[138:139], v226 offset:60480
	ds_read_b64_tr_b16 v[248:249], v226 offset:60544
	v_mov_b64_e32 v[194:195], v[178:179]
	ds_read_b64_tr_b16 v[178:179], v226 offset:60608
	ds_read_b64_tr_b16 v[136:137], v226 offset:62976
	ds_read_b64_tr_b16 v[140:141], v226 offset:63040
	ds_read_b64_tr_b16 v[250:251], v226 offset:63104
	ds_read_b64_tr_b16 v[180:181], v226 offset:63168
	v_mov_b64_e32 v[222:223], v[216:217]
	v_mov_b64_e32 v[216:217], v[176:177]
	v_add_f32_e32 v16, v9, v16
	v_exp_f32_e32 v13, v13
	s_waitcnt lgkmcnt(14)
; #define SCHED_FENCE() __builtin_amdgcn_sched_barrier(0)
; #define LOADB(tt) do { const char* kp_ = kgp + (size_t)(tt) * tstep; const char* vp_ = vgp + (size_t)(tt) * tstep; kb0 = *(const u32x4*)kp_; kb1 = *(const u32x4*)(kp_ + 16); vb0 = *(const u32x4*)vp_; vb1 = *(const u32x4*)(vp_ + 16); } while (0)
; template <int NC, bool DIAG>
; __device__ __forceinline__ void attn_tile(f32x16 (&O)[4], float& l, const bf16x8* Q, const LAS char* Kb, const LAS char* Vb, int r32, int hi, int lane, float qd, int k0, int qw, float nslope, float negM0) {
;     ...
;     pvmm32(O, P0, vf0);
;     if (NC == 2 && DIAG) { const float nd = (k1 == qw) ? nslope : 0.f;
; #pragma unroll
;         for (int r = 0; r < 16; ++r) S1[r] = fmaf(nd, fabsf(qd - (float)k1 - (float)((r & 3) + 8 * (r >> 2))), S1[r]); }
;     soft32<0>(S1, P1, l, 0.f, 0.f);
;     if (NC == 2) {
;     vload16<0>(vf1, Vb + 32 * VP, lane);
;     SCHED_FENCE();
;     vload16<1>(vf1, Vb + 32 * VP, lane);
;     } else {
;     vload32(vf1, Vb + 32 * VP, lane);
;     SCHED_FENCE();
;     }
;     pvmm32(O, P1, vf1);
; template <int NC>
; __device__ __forceinline__ void attn_shared_unit(LAS char* lds, bf16* qbase, const bf16* Kg, const bf16* Vg, int kvp, int nt, int qpos, int qw, float nslope, float negM0, float lam, const float* subln, int wave_id) {
;     ...
;             if (t + 3 < t_hi) LOADB(t + 3);
	v_mfma_f32_32x32x16_bf16 v[146:161], v[36:39], v[174:177], v[146:161]
	v_mov_b64_e32 v[214:215], v[174:175]
	v_mov_b64_e32 v[176:177], v[172:173]
	v_add_f32_e32 v16, v10, v16
	v_exp_f32_e32 v14, v14
	v_mov_b64_e32 v[174:175], v[170:171]
	v_mov_b64_e32 v[172:173], v[168:169]
	v_add_f32_e32 v16, v11, v16
	v_exp_f32_e32 v15, v15
	v_mov_b64_e32 v[170:171], v[166:167]
	v_mov_b64_e32 v[168:169], v[164:165]
	v_add_f32_e32 v16, v12, v16
	v_mov_b64_e32 v[166:167], v[162:163]
	s_waitcnt vmcnt(0)
	v_mov_b64_e32 v[162:163], v[210:211]
	v_add_f32_e32 v16, v13, v16
	v_mov_b64_e32 v[164:165], v[212:213]
	v_mov_b64_e32 v[212:213], v[204:205]
	v_add_f32_e32 v16, v14, v16
	v_mov_b64_e32 v[210:211], v[202:203]
	v_mov_b64_e32 v[204:205], v[192:193]
	v_add_f32_e32 v16, v15, v16
	v_mov_b64_e32 v[202:203], v[190:191]
	v_cvt_pk_bf16_f32 v190, v8, v9
	v_cvt_pk_bf16_f32 v191, v10, v11
	v_cvt_pk_bf16_f32 v192, v12, v13
	v_cvt_pk_bf16_f32 v193, v14, v15
	v_cvt_pk_bf16_f32 v130, v0, v1
	v_cvt_pk_bf16_f32 v131, v2, v3
	v_cvt_pk_bf16_f32 v132, v4, v5
	v_cvt_pk_bf16_f32 v133, v6, v7
	v_exp_f32_e32 v142, v146
	v_exp_f32_e32 v143, v147
	v_exp_f32_e32 v146, v148
	v_exp_f32_e32 v147, v149
	v_add_f32_e32 v0, v16, v142
	v_exp_f32_e32 v148, v150
	v_add_f32_e32 v0, v143, v0
	v_exp_f32_e32 v149, v151
	v_add_f32_e32 v0, v146, v0
	v_exp_f32_e32 v150, v152
	v_add_f32_e32 v0, v147, v0
	v_exp_f32_e32 v151, v153
	v_add_f32_e32 v0, v148, v0
	v_exp_f32_e32 v153, v154
	s_waitcnt lgkmcnt(11)
	v_mfma_f32_32x32x16_bf16 v[48:63], v[24:27], v[130:133], v[64:79]
	v_add_f32_e32 v0, v149, v0
	v_exp_f32_e32 v154, v155
	v_add_f32_e32 v0, v150, v0
	v_exp_f32_e32 v155, v156
	v_add_f32_e32 v152, v151, v0
	v_exp_f32_e32 v156, v157
	v_exp_f32_e32 v157, v159
	s_waitcnt lgkmcnt(10)
	v_mfma_f32_32x32x16_bf16 v[32:47], v[236:239], v[130:133], v[80:95]
	s_waitcnt lgkmcnt(9)
	v_mfma_f32_32x32x16_bf16 v[16:31], v[240:243], v[130:133], v[96:111]
	s_waitcnt lgkmcnt(8)
	v_mfma_f32_32x32x16_bf16 v[0:15], v[244:247], v[130:133], v[112:127]
	v_add_f32_e32 v130, v153, v152
	v_exp_f32_e32 v152, v158
	v_add_f32_e32 v130, v154, v130
	v_add_f32_e32 v130, v155, v130
	v_add_f32_e32 v130, v156, v130
	v_add_f32_e32 v130, v152, v130
	v_add_f32_e32 v130, v157, v130
	s_waitcnt lgkmcnt(3)
	v_mfma_f32_32x32x16_bf16 v[48:63], v[134:137], v[190:193], v[48:63]
	v_cvt_pk_bf16_f32 v131, v146, v147
	v_cvt_pk_bf16_f32 v132, v148, v149
	v_cvt_pk_bf16_f32 v133, v150, v151
	v_cvt_pk_bf16_f32 v134, v153, v154
	v_cvt_pk_bf16_f32 v135, v155, v156
	v_cvt_pk_bf16_f32 v136, v152, v157
	v_exp_f32_e32 v137, v160
	s_waitcnt lgkmcnt(2)
	v_mfma_f32_32x32x16_bf16 v[32:47], v[138:141], v[190:193], v[32:47]
	ds_read_b64_tr_b16 v[138:139], v221
	ds_read_b64_tr_b16 v[146:147], v221 offset:64
	ds_read_b64_tr_b16 v[150:151], v221 offset:128
	ds_read_b64_tr_b16 v[154:155], v221 offset:192
	ds_read_b64_tr_b16 v[140:141], v221 offset:2560
	ds_read_b64_tr_b16 v[148:149], v221 offset:2624
	ds_read_b64_tr_b16 v[152:153], v221 offset:2688
	ds_read_b64_tr_b16 v[156:157], v221 offset:2752
	v_exp_f32_e32 v158, v161
	v_add_f32_e32 v130, v137, v130
	v_add_f32_e32 v229, v158, v130
	v_cvt_pk_bf16_f32 v130, v142, v143
	s_waitcnt lgkmcnt(9)
	v_mfma_f32_32x32x16_bf16 v[16:31], v[248:251], v[190:193], v[16:31]
	v_fma_f32 v142, v218, v234, v254
	v_cvt_pk_bf16_f32 v137, v137, v158
	s_waitcnt lgkmcnt(8)
	v_mfma_f32_32x32x16_bf16 v[0:15], v[178:181], v[190:193], v[0:15]
	v_mov_b64_e32 v[190:191], v[202:203]
	v_mov_b64_e32 v[192:193], v[204:205]
	v_mov_b64_e32 v[202:203], v[210:211]
	v_mov_b64_e32 v[204:205], v[212:213]
	v_mov_b64_e32 v[212:213], v[164:165]
	v_mov_b64_e32 v[178:179], v[194:195]
	v_mov_b64_e32 v[210:211], v[162:163]
	v_mov_b64_e32 v[162:163], v[166:167]
	v_mov_b64_e32 v[180:181], v[196:197]
	v_mov_b64_e32 v[196:197], v[184:185]
	v_mov_b64_e32 v[164:165], v[168:169]
	v_mov_b64_e32 v[166:167], v[170:171]
	v_mov_b64_e32 v[194:195], v[182:183]
	v_mov_b64_e32 v[182:183], v[186:187]
	v_mov_b64_e32 v[168:169], v[172:173]
	v_mov_b64_e32 v[170:171], v[174:175]
	v_mov_b64_e32 v[184:185], v[188:189]
	v_mov_b64_e32 v[186:187], v[198:199]
	v_mov_b64_e32 v[172:173], v[176:177]
	v_mov_b64_e32 v[174:175], v[214:215]
	v_mov_b64_e32 v[188:189], v[200:201]
	v_mov_b64_e32 v[198:199], v[206:207]
	v_mov_b64_e32 v[176:177], v[216:217]
	v_mov_b64_e32 v[216:217], v[222:223]
	v_mov_b64_e32 v[200:201], v[208:209]
	v_mov_b64_e32 v[208:209], v[230:231]
	s_cmp_ge_i32 s88, s57
	s_cbranch_scc1 .Lmy_a_ldb_skip1
	global_load_dwordx4 v[182:185], v[216:217], off offset:-1024
	global_load_dwordx4 v[186:189], v[216:217], off offset:-1040
	global_load_dwordx4 v[198:201], v[216:217], off
	global_load_dwordx4 v[210:213], v[216:217], off offset:-16
.Lmy_a_ldb_skip1:
	s_waitcnt lgkmcnt(3)
	v_mfma_f32_32x32x16_bf16 v[48:63], v[138:141], v[130:133], v[48:63]
	ds_read_b64_tr_b16 v[140:141], v221 offset:7680
	s_waitcnt lgkmcnt(3)
	v_mfma_f32_32x32x16_bf16 v[32:47], v[146:149], v[130:133], v[32:47]
	s_waitcnt lgkmcnt(2)
	v_mfma_f32_32x32x16_bf16 v[16:31], v[150:153], v[130:133], v[16:31]
	s_waitcnt lgkmcnt(1)
	v_mfma_f32_32x32x16_bf16 v[0:15], v[154:157], v[130:133], v[0:15]
	ds_read_b64_tr_b16 v[138:139], v221 offset:5120
	ds_read_b64_tr_b16 v[130:131], v221 offset:5184
	ds_read_b64_tr_b16 v[146:147], v221 offset:5248
	ds_read_b64_tr_b16 v[150:151], v221 offset:5312
	ds_read_b64_tr_b16 v[132:133], v221 offset:7744
	ds_read_b64_tr_b16 v[148:149], v221 offset:7808
	ds_read_b64_tr_b16 v[152:153], v221 offset:7872
	s_waitcnt lgkmcnt(6)
	v_mfma_f32_32x32x16_bf16 v[48:63], v[138:141], v[134:137], v[48:63]
	s_waitcnt lgkmcnt(2)
	v_mfma_f32_32x32x16_bf16 v[32:47], v[130:133], v[134:137], v[32:47]
	s_waitcnt lgkmcnt(1)
	v_mfma_f32_32x32x16_bf16 v[16:31], v[146:149], v[134:137], v[16:31]
	s_waitcnt lgkmcnt(0)
	v_mfma_f32_32x32x16_bf16 v[0:15], v[150:153], v[134:137], v[0:15]
	s_cbranch_execz .LBB0_285

; #define LAS __attribute__((address_space(3)))
; #define LOADB(tt) do { const char* kp_ = kgp + (size_t)(tt) * tstep; const char* vp_ = vgp + (size_t)(tt) * tstep; kb0 = *(const u32x4*)kp_; kb1 = *(const u32x4*)(kp_ + 16); vb0 = *(const u32x4*)vp_; vb1 = *(const u32x4*)(vp_ + 16); } while (0)
; template <int NC>
; __device__ __forceinline__ void attn_shared_unit(LAS char* lds, bf16* qbase, const bf16* Kg, const bf16* Vg, int kvp, int nt, int qpos, int qw, float nslope, float negM0, float lam, const float* subln, int wave_id) {
;     ...
;         {
;             if (t + 3 < t_hi) LOADB(t + 3);
;             int k0v = (t + 1) * 64; asm volatile("" : "+s"(k0v));
;             const LAS char* Kb = lds + BUFB + cm * 128; const LAS char* Vb = lds + BUFB + 64 * KP;
;             if (t + 1 == td) attn_tile<NC, true>(O, l, Q, Kb, Vb, r32, hi, lane, qd, k0v, qw, nslope, negM0);
;             else attn_tile<NC, false>(O, l, Q, Kb, Vb, r32, hi, lane, qd, k0v, qw, nslope, negM0);
.LBB0_285:
	s_cmp_ge_i32 s88, s57
	s_cbranch_scc1 .Lmy_a_ldb_skip0
	global_load_dwordx4 v[182:185], v[216:217], off offset:-1024
	global_load_dwordx4 v[186:189], v[216:217], off offset:-1040
	global_load_dwordx4 v[198:201], v[216:217], off
	global_load_dwordx4 v[210:213], v[216:217], off offset:-16

; __device__ __forceinline__ int tid_fresh(int wave) { return wave * 64 + lane_id_fresh(); }
; #define LOADA(tt) do { const char* kp_ = kgp + (size_t)(tt) * tstep; const char* vp_ = vgp + (size_t)(tt) * tstep; ka0 = *(const u32x4*)kp_; ka1 = *(const u32x4*)(kp_ + 16); va0 = *(const u32x4*)vp_; va1 = *(const u32x4*)(vp_ + 16); } while (0)
; #define WRITEA(buf) do { LAS char* kw_ = lds + (buf) * BUFB + lrow * KP + lcb; LAS char* vw_ = lds + (buf) * BUFB + 64 * KP + lrow * VP + lcb; *(LAS u32x4*)kw_ = ka0; *(LAS u32x4*)(kw_ + 16) = ka1; *(LAS u32x4*)vw_ = va0; *(LAS u32x4*)(vw_ + 16) = va1; } while (0)
; template <int NC>
; __device__ __forceinline__ void attn_shared_unit(LAS char* lds, bf16* qbase, const bf16* Kg, const bf16* Vg, int kvp, int nt, int qpos, int qw, float nslope, float negM0, float lam, const float* subln, int wave_id) {
;     const int wv = wave_id, tid = pg8::tid_fresh(wave_id);
;     const int lane = tid & 63, r32 = lane & 31, hi = lane >> 5;
;     const int cm = (NC == 2) ? (wv & 1) : 0;
;     constexpr int NQ = (NC == 2) ? 4 : 8;
;     bf16x8 Q[NQ];
;     { const bf16* qrow0 = qbase + (size_t)r32 * LDQ;
; #pragma unroll
;     for (int ks = 0; ks < NQ; ++ks) Q[ks] = *(const bf16x8*)(qrow0 + cm * 64 + 16 * ks + 8 * hi); }
;     f32x16 O[4]; float l = 0.f;
; #pragma unroll
;     for (int db = 0; db < 4; ++db) zero16(O[db]);
;     const int lrow = tid >> 3, lcb = (tid & 7) * 32;
;     const char* kgp = (const char*)(Kg + (size_t)lrow * kvp) + lcb; const char* vgp = (const char*)(Vg + (size_t)lrow * kvp) + lcb;
;     const size_t tstep = (size_t)64 * kvp * 2;
;     u32x4 ka0, ka1, va0, va1, kb0, kb1, vb0, vb1;
;     ...
;     constexpr int BUFB = 64 * KP + 64 * VP;
;     ...
;     LOADA(0);
;     __syncthreads();
;     WRITEA(0);
;     __syncthreads();
.LBB0_295:
	s_lshl_b32 s10, s7, 1
	s_and_b32 s47, s10, 0x300
	s_mov_b32 s10, 0
	s_ashr_i32 s20, s33, 5
	s_lshl_b32 s10, s33, 8
	s_and_b32 s44, s10, 0x700
	s_ashr_i32 s21, s20, 31
	s_lshl_b64 s[10:11], s[20:21], 11
	s_add_i32 s44, s44, s6
	s_add_u32 s10, s10, s44
	s_addc_u32 s11, s11, 0
	s_mulk_i32 s11, 0x3400
	s_mul_hi_u32 s44, s10, 0x3400
	s_add_i32 s44, s44, s11
	s_mulk_i32 s10, 0x3400
	s_add_u32 s10, s18, s10
	s_addc_u32 s11, s19, s44
	s_lshl_b32 s44, s33, 5
	s_and_b32 s44, s44, 0x300
	s_add_u32 s10, s10, s44
	s_addc_u32 s11, s11, 0
	s_add_u32 s10, s10, 0x3000
	s_addc_u32 s11, s11, 0
	s_lshl_b64 s[20:21], s[20:21], 19
	s_add_u32 s45, s74, s20
	s_addc_u32 s46, s75, s21
	s_add_u32 s44, s45, s44
	s_addc_u32 s45, s46, 0
	s_mov_b32 s46, 0
	v_mov_b32_e32 v163, v161
	v_mbcnt_lo_u32_b32 v16, -1, s46
	v_mbcnt_hi_u32_b32 v32, -1, v16
	v_add_u32_e32 v16, s80, v32
	v_ashrrev_i32_e32 v26, 3, v16
	v_and_b32_e32 v33, 31, v32
	v_ashrrev_i32_e32 v27, 31, v26
	v_mul_u32_u24_e32 v30, 0x1a00, v33
	v_lshlrev_b32_e32 v16, 5, v32
	v_lshlrev_b64 v[28:29], 11, v[26:27]
	v_and_b32_e32 v27, 32, v32
	v_lshlrev_b32_e32 v160, 1, v30
	v_and_b32_e32 v162, 0xe0, v16
	v_lshl_add_u64 v[16:17], s[44:45], 0, v[28:29]
	v_lshl_add_u64 v[30:31], s[10:11], 0, v[160:161]
	v_lshrrev_b32_e32 v160, 1, v27
	v_lshl_add_u64 v[16:17], v[16:17], 0, v[162:163]
	v_lshl_add_u64 v[30:31], v[30:31], 0, v[160:161]
	global_load_dwordx4 v[112:115], v[16:17], off
	global_load_dwordx4 v[116:119], v[16:17], off offset:16
	global_load_dwordx4 v[120:123], v[16:17], off offset:1024
	global_load_dwordx4 v[124:127], v[16:17], off offset:1040
	global_load_dwordx4 v[128:131], v[30:31], off
	global_load_dwordx4 v[132:135], v[30:31], off offset:32
	global_load_dwordx4 v[136:139], v[30:31], off offset:64
	global_load_dwordx4 v[140:143], v[30:31], off offset:96
	global_load_dwordx4 v[144:147], v[30:31], off offset:128
	global_load_dwordx4 v[148:151], v[30:31], off offset:160
	global_load_dwordx4 v[152:155], v[30:31], off offset:192
	global_load_dwordx4 v[156:159], v[30:31], off offset:224
	v_and_b32_e32 v35, 16, v32
	v_lshlrev_b32_e32 v30, 2, v32
	v_bfe_u32 v34, v32, 2, 2
	v_lshrrev_b32_e32 v27, 3, v32
	v_and_or_b32 v30, v30, 12, v35
	v_mul_lo_u32 v167, v26, s26
	v_and_or_b32 v27, v27, 4, v34
	v_lshlrev_b32_e32 v170, 1, v30
	v_add3_u32 v30, 0, v167, v162
	v_lshl_add_u64 v[28:29], s[20:21], 0, v[28:29]
	v_mul_lo_u32 v168, v26, s27
	v_mul_u32_u24_e32 v169, 0x140, v27
	v_mad_u64_u32 v[26:27], s[48:49], v26, 48, v[30:31]
	v_or3_b32 v28, v28, s47, v162
	s_mov_b32 s44, 0
	s_mov_b32 s46, 0
	v_mov_b32_e32 v163, 0
	v_mov_b32_e32 v16, 0
	v_mov_b32_e32 v17, v161
	v_mov_b32_e32 v18, v161
	v_mov_b32_e32 v19, v161
	v_mov_b32_e32 v20, v161
	v_mov_b32_e32 v21, v161
	v_mov_b32_e32 v22, v161
	v_mov_b32_e32 v23, v161
	v_mov_b32_e32 v24, v161
	v_mov_b32_e32 v25, v161
	v_mul_u32_u24_e32 v166, 0x110, v33
	v_lshl_add_u64 v[164:165], s[4:5], 0, v[28:29]
	s_barrier
	v_mov_b32_e32 v27, v161
	v_mov_b32_e32 v28, v161
	v_mov_b32_e32 v29, v161
	v_mov_b32_e32 v31, v161
	v_mov_b32_e32 v32, 0
	v_mov_b32_e32 v33, v161
	v_mov_b32_e32 v34, v161
	v_mov_b32_e32 v35, v161
	v_mov_b32_e32 v36, v161
	v_mov_b32_e32 v37, v161
	v_mov_b32_e32 v38, v161
	v_mov_b32_e32 v39, v161
	v_mov_b32_e32 v40, v161
	v_mov_b32_e32 v41, v161
	v_mov_b32_e32 v42, v161
	v_mov_b32_e32 v43, v161
	v_mov_b32_e32 v44, v161
	v_mov_b32_e32 v45, v161
	v_mov_b32_e32 v46, v161
	v_mov_b32_e32 v47, v161
	v_mov_b32_e32 v48, 0
	v_mov_b32_e32 v49, v161
	v_mov_b32_e32 v50, v161
	v_mov_b32_e32 v51, v161
	v_mov_b32_e32 v52, v161
	s_waitcnt vmcnt(11)
	ds_write_b128 v30, v[112:115]
	s_waitcnt vmcnt(10)
	ds_write_b128 v30, v[116:119] offset:16
	s_waitcnt vmcnt(9)
	ds_write_b128 v26, v[120:123] offset:17408
	s_waitcnt vmcnt(8)
	ds_write_b128 v26, v[124:127] offset:17424
	v_mov_b32_e32 v26, v161
	v_mov_b32_e32 v30, v161
	v_mov_b32_e32 v53, v161
	v_mov_b32_e32 v54, v161
	v_mov_b32_e32 v55, v161
	v_mov_b32_e32 v56, v161
	v_mov_b32_e32 v57, v161
	v_mov_b32_e32 v58, v161
	v_mov_b32_e32 v59, v161
	v_mov_b32_e32 v60, v161
	v_mov_b32_e32 v61, v161
	v_mov_b32_e32 v62, v161
	v_mov_b32_e32 v63, v161
	v_mov_b32_e32 v64, 0
	v_mov_b32_e32 v65, v161
	v_mov_b32_e32 v66, v161
	v_mov_b32_e32 v67, v161
	v_mov_b32_e32 v68, v161
	v_mov_b32_e32 v69, v161
	v_mov_b32_e32 v70, v161
	v_mov_b32_e32 v71, v161
	v_mov_b32_e32 v72, v161
	v_mov_b32_e32 v73, v161
	v_mov_b32_e32 v74, v161
	v_mov_b32_e32 v75, v161
	v_mov_b32_e32 v76, v161
	v_mov_b32_e32 v77, v161
	v_mov_b32_e32 v78, v161
	v_mov_b32_e32 v79, v161
	s_waitcnt vmcnt(0) lgkmcnt(0)
	s_barrier
	s_cmp_lg_u32 s46, 3
	s_cselect_b64 s[20:21], -1, 0
	s_cmp_eq_u32 s46, 3
	s_cbranch_scc1 .LBB0_298
	s_branch .LBB0_297

; #define LAS __attribute__((address_space(3)))
; #define SCHED_FENCE() __builtin_amdgcn_sched_barrier(0)
; #define LOADA(tt) do { const char* kp_ = kgp + (size_t)(tt) * tstep; const char* vp_ = vgp + (size_t)(tt) * tstep; ka0 = *(const u32x4*)kp_; ka1 = *(const u32x4*)(kp_ + 16); va0 = *(const u32x4*)vp_; va1 = *(const u32x4*)(vp_ + 16); } while (0)
; #define WRITEA(buf) do { LAS char* kw_ = lds + (buf) * BUFB + lrow * KP + lcb; LAS char* vw_ = lds + (buf) * BUFB + 64 * KP + lrow * VP + lcb; *(LAS u32x4*)kw_ = ka0; *(LAS u32x4*)(kw_ + 16) = ka1; *(LAS u32x4*)vw_ = va0; *(LAS u32x4*)(vw_ + 16) = va1; } while (0)
; template <int NC, bool DIAG>
; __device__ __forceinline__ void attn_tile(f32x16 (&O)[4], float& l, const bf16x8* Q, const LAS char* Kb, const LAS char* Vb, int r32, int hi, int lane, float qd, int k0, int qw, float nslope, float negM0) {
;     ...
;         bf16x8 kf[NQ];
;         kload32<NQ>(kf, Kb, r32, hi);
;         SCHED_FENCE();
;         qkmm32<NQ>(S0, kf, Q);
;         kload32<NQ>(kf, Kb + 32 * KP, r32, hi);
;         vload32(vf0, Vb, lane);
;         SCHED_FENCE();
;         qkmm32<NQ>(S1, kf, Q);
;         soft32<0>(S0, P0, l, 0.f, 0.f);
;         SCHED_FENCE();
;     }
;     pvmm32(O, P0, vf0);
;     if (NC == 2 && DIAG) { const float nd = (k1 == qw) ? nslope : 0.f;
; #pragma unroll
;         for (int r = 0; r < 16; ++r) S1[r] = fmaf(nd, fabsf(qd - (float)k1 - (float)((r & 3) + 8 * (r >> 2))), S1[r]); }
;     soft32<0>(S1, P1, l, 0.f, 0.f);
;     if (NC == 2) {
;     vload16<0>(vf1, Vb + 32 * VP, lane);
;     SCHED_FENCE();
;     vload16<1>(vf1, Vb + 32 * VP, lane);
;     } else {
;     vload32(vf1, Vb + 32 * VP, lane);
;     SCHED_FENCE();
;     }
;     pvmm32(O, P1, vf1);
; template <int NC>
; __device__ __forceinline__ void attn_shared_unit(LAS char* lds, bf16* qbase, const bf16* Kg, const bf16* Vg, int kvp, int nt, int qpos, int qw, float nslope, float negM0, float lam, const float* subln, int wave_id) {
;     ...
;     for (int t = 0; t < nt; ++t) {
;         const bool more = (t + 1 < nt);
;         if (more) LOADA(t + 1);
;         int k0v = t * 64; asm volatile("" : "+s"(k0v));
;         const LAS char* Kb = lds + (t & 1) * BUFB; const LAS char* Vb = lds + (t & 1) * BUFB + 64 * KP;
;         attn_tile<NC, false>(O, l, Q, Kb, Vb, r32, hi, lane, qd, k0v, qw, nslope, negM0);
;         if (more) WRITEA((t + 1) & 1);
;         __syncthreads();
.LBB0_298:
	s_add_i32 s45, s46, 1
	s_bitcmp1_b32 s46, 0
	s_cselect_b32 s46, 0x9400, 0
	s_add_i32 s46, s46, 0
	s_mov_b32 s47, s44
	v_add3_u32 v171, s46, v166, v160
	ds_read_b128 v[96:99], v171
	ds_read_b128 v[100:103], v171 offset:32
	ds_read_b128 v[104:107], v171 offset:64
	ds_read_b128 v[108:111], v171 offset:96
	ds_read_b128 v[172:175], v171 offset:128
	ds_read_b128 v[176:179], v171 offset:160
	ds_read_b128 v[180:183], v171 offset:192
	ds_read_b128 v[184:187], v171 offset:224
	s_waitcnt lgkmcnt(7)
	v_mfma_f32_32x32x16_bf16 v[80:95], v[96:99], v[128:131], v[0:15]
	ds_read_b128 v[188:191], v171 offset:8704
	ds_read_b128 v[192:195], v171 offset:8736
	s_waitcnt lgkmcnt(8)
	v_mfma_f32_32x32x16_bf16 v[80:95], v[100:103], v[132:135], v[80:95]
	s_waitcnt lgkmcnt(7)
	v_mfma_f32_32x32x16_bf16 v[80:95], v[104:107], v[136:139], v[80:95]
	s_waitcnt lgkmcnt(6)
	v_mfma_f32_32x32x16_bf16 v[80:95], v[108:111], v[140:143], v[80:95]
	s_waitcnt lgkmcnt(5)
	v_mfma_f32_32x32x16_bf16 v[80:95], v[172:175], v[144:147], v[80:95]
	ds_read_b128 v[172:175], v171 offset:8768
	ds_read_b128 v[196:199], v171 offset:8800
	ds_read_b128 v[200:203], v171 offset:8832
	ds_read_b128 v[204:207], v171 offset:8864
	ds_read_b128 v[208:211], v171 offset:8896
	ds_read_b128 v[212:215], v171 offset:8928
	v_add3_u32 v171, s46, v169, v170
	s_waitcnt lgkmcnt(10)
	v_mfma_f32_32x32x16_bf16 v[80:95], v[176:179], v[148:151], v[80:95]
	ds_read_b64_tr_b16 v[176:177], v171 offset:17408
	ds_read_b64_tr_b16 v[216:217], v171 offset:17472
	ds_read_b64_tr_b16 v[220:221], v171 offset:17536
	ds_read_b64_tr_b16 v[224:225], v171 offset:17600
	ds_read_b64_tr_b16 v[178:179], v171 offset:19968
	ds_read_b64_tr_b16 v[218:219], v171 offset:20032
	ds_read_b64_tr_b16 v[222:223], v171 offset:20096
	ds_read_b64_tr_b16 v[226:227], v171 offset:20160
	s_waitcnt lgkmcnt(14)
	v_mfma_f32_32x32x16_bf16 v[80:95], v[180:183], v[152:155], v[80:95]
	ds_read_b64_tr_b16 v[180:181], v171 offset:22528
	ds_read_b64_tr_b16 v[228:229], v171 offset:22592
	ds_read_b64_tr_b16 v[232:233], v171 offset:22656
	ds_read_b64_tr_b16 v[236:237], v171 offset:22720
	ds_read_b64_tr_b16 v[182:183], v171 offset:25088
	ds_read_b64_tr_b16 v[230:231], v171 offset:25152
	ds_read_b64_tr_b16 v[234:235], v171 offset:25216
	ds_read_b64_tr_b16 v[238:239], v171 offset:25280
	s_nop 0
	v_mfma_f32_32x32x16_bf16 v[80:95], v[184:187], v[156:159], v[80:95]
	v_mfma_f32_32x32x16_bf16 v[96:111], v[188:191], v[128:131], v[0:15]
	s_nop 10
	v_exp_f32_e32 v80, v80
	v_exp_f32_e32 v81, v81
	v_exp_f32_e32 v82, v82
	v_exp_f32_e32 v83, v83
	v_exp_f32_e32 v84, v84
	v_exp_f32_e32 v85, v85
	v_exp_f32_e32 v86, v86
	v_mfma_f32_32x32x16_bf16 v[96:111], v[192:195], v[132:135], v[96:111]
	v_exp_f32_e32 v87, v87
	v_exp_f32_e32 v88, v88
	v_exp_f32_e32 v89, v89
	v_exp_f32_e32 v90, v90
	v_exp_f32_e32 v91, v91
	v_exp_f32_e32 v92, v92
	v_exp_f32_e32 v93, v93
	s_waitcnt lgkmcnt(14)
	v_mfma_f32_32x32x16_bf16 v[96:111], v[172:175], v[136:139], v[96:111]
	v_exp_f32_e32 v94, v94
	v_exp_f32_e32 v95, v95
	v_cvt_pk_bf16_f32 v172, v80, v81
	v_cvt_pk_bf16_f32 v173, v82, v83
	v_cvt_pk_bf16_f32 v174, v84, v85
	v_cvt_pk_bf16_f32 v175, v86, v87
	v_cvt_pk_bf16_f32 v184, v88, v89
	v_mfma_f32_32x32x16_bf16 v[96:111], v[196:199], v[140:143], v[96:111]
	v_cvt_pk_bf16_f32 v185, v90, v91
	v_cvt_pk_bf16_f32 v186, v92, v93
	v_cvt_pk_bf16_f32 v187, v94, v95
	v_mfma_f32_32x32x16_bf16 v[96:111], v[200:203], v[144:147], v[96:111]
	v_mfma_f32_32x32x16_bf16 v[96:111], v[204:207], v[148:151], v[96:111]
	v_mfma_f32_32x32x16_bf16 v[96:111], v[208:211], v[152:155], v[96:111]
	v_mfma_f32_32x32x16_bf16 v[96:111], v[212:215], v[156:159], v[96:111]
	s_waitcnt lgkmcnt(11)
	v_mfma_f32_32x32x16_bf16 v[64:79], v[176:179], v[172:175], v[64:79]
	s_nop 9
	v_exp_f32_e32 v96, v96
	v_exp_f32_e32 v97, v97
	v_exp_f32_e32 v98, v98
	v_exp_f32_e32 v99, v99
	v_exp_f32_e32 v100, v100
	v_exp_f32_e32 v101, v101
	v_exp_f32_e32 v102, v102
	s_waitcnt lgkmcnt(10)
	v_mfma_f32_32x32x16_bf16 v[48:63], v[216:219], v[172:175], v[48:63]
	v_exp_f32_e32 v103, v103
	v_exp_f32_e32 v104, v104
	v_exp_f32_e32 v105, v105
	v_exp_f32_e32 v106, v106
	v_exp_f32_e32 v107, v107
	v_exp_f32_e32 v108, v108
	v_exp_f32_e32 v109, v109
	s_waitcnt lgkmcnt(9)
	v_mfma_f32_32x32x16_bf16 v[32:47], v[220:223], v[172:175], v[32:47]
	v_exp_f32_e32 v110, v110
	v_exp_f32_e32 v111, v111
	v_cvt_pk_bf16_f32 v176, v104, v105
	v_cvt_pk_bf16_f32 v177, v106, v107
	v_cvt_pk_bf16_f32 v178, v108, v109
	v_cvt_pk_bf16_f32 v179, v110, v111
	s_waitcnt lgkmcnt(8)
	v_mfma_f32_32x32x16_bf16 v[16:31], v[224:227], v[172:175], v[16:31]
	v_cvt_pk_bf16_f32 v172, v96, v97
	v_cvt_pk_bf16_f32 v173, v98, v99
	v_cvt_pk_bf16_f32 v174, v100, v101
	v_cvt_pk_bf16_f32 v175, v102, v103
	s_waitcnt lgkmcnt(3)
	v_mfma_f32_32x32x16_bf16 v[64:79], v[180:183], v[184:187], v[64:79]
	ds_read_b64_tr_b16 v[180:181], v171 offset:27648
	ds_read_b64_tr_b16 v[188:189], v171 offset:27712
	ds_read_b64_tr_b16 v[192:193], v171 offset:27776
	ds_read_b64_tr_b16 v[196:197], v171 offset:27840
	ds_read_b64_tr_b16 v[182:183], v171 offset:30208
	ds_read_b64_tr_b16 v[190:191], v171 offset:30272
	ds_read_b64_tr_b16 v[194:195], v171 offset:30336
	ds_read_b64_tr_b16 v[198:199], v171 offset:30400
	ds_read_b64_tr_b16 v[200:201], v171 offset:32768
	ds_read_b64_tr_b16 v[204:205], v171 offset:32832
	ds_read_b64_tr_b16 v[208:209], v171 offset:32896
	ds_read_b64_tr_b16 v[212:213], v171 offset:32960
	ds_read_b64_tr_b16 v[202:203], v171 offset:35328
	ds_read_b64_tr_b16 v[206:207], v171 offset:35392
	ds_read_b64_tr_b16 v[210:211], v171 offset:35456
	ds_read_b64_tr_b16 v[214:215], v171 offset:35520
	s_waitcnt lgkmcnt(14)
	v_mfma_f32_32x32x16_bf16 v[48:63], v[228:231], v[184:187], v[48:63]
	v_mfma_f32_32x32x16_bf16 v[32:47], v[232:235], v[184:187], v[32:47]
	v_mfma_f32_32x32x16_bf16 v[16:31], v[236:239], v[184:187], v[16:31]
	s_waitcnt lgkmcnt(11)
	v_mfma_f32_32x32x16_bf16 v[64:79], v[180:183], v[172:175], v[64:79]
	s_andn2_b64 vcc, exec, s[20:21]
	s_waitcnt lgkmcnt(10)
	v_mfma_f32_32x32x16_bf16 v[48:63], v[188:191], v[172:175], v[48:63]
	s_waitcnt lgkmcnt(9)
	v_mfma_f32_32x32x16_bf16 v[32:47], v[192:195], v[172:175], v[32:47]
	s_waitcnt lgkmcnt(8)
	v_mfma_f32_32x32x16_bf16 v[16:31], v[196:199], v[172:175], v[16:31]
	s_waitcnt lgkmcnt(3)
	v_mfma_f32_32x32x16_bf16 v[64:79], v[200:203], v[176:179], v[64:79]
	s_waitcnt lgkmcnt(2)
	v_mfma_f32_32x32x16_bf16 v[48:63], v[204:207], v[176:179], v[48:63]
	s_waitcnt lgkmcnt(1)
	v_mfma_f32_32x32x16_bf16 v[32:47], v[208:211], v[176:179], v[32:47]
	s_waitcnt lgkmcnt(0)
	v_mfma_f32_32x32x16_bf16 v[16:31], v[212:215], v[176:179], v[16:31]
	s_cbranch_vccnz .LBB0_300
	s_bitcmp1_b32 s45, 0
	s_cselect_b32 s20, 0x9400, 0
	s_add_i32 s20, s20, 0
	v_add3_u32 v171, s20, v167, v162
	v_add3_u32 v172, s20, v168, v162
	s_waitcnt vmcnt(0)
	ds_write_b128 v171, v[112:115]
	ds_write_b128 v171, v[116:119] offset:16
	ds_write_b128 v172, v[120:123] offset:17408
	ds_write_b128 v172, v[124:127] offset:17424

; __device__ __forceinline__ int tid_fresh(int wave) { return wave * 64 + lane_id_fresh(); }
; #define LAS __attribute__((address_space(3)))
; template <bool SEG2>
; __device__ __forceinline__ void attn_b_block_unit(LAS char* lds, bf16* R, float* LB, int b, int g, int j, int res0, int q0, int dil, float nslope, float negM0, int wave_id) {
;     const int tid = pg8::tid_fresh(wave_id), lane = tid & 63, r32 = lane & 31, hi = lane >> 5;
;     const int sub_len = SEQ / dil, hcol = (g * 4 + j) * 128;
;     const int wres = SEG2 ? res0 + (wave_id >> 2) : res0;
;     const int qs = SEG2 ? 32 * (wave_id & 3) : q0 + 32 * wave_id;
;     const size_t rowb = (size_t)b * SEQ;
;     bf16x8 Q[8];
;     { const bf16* qr = R + (rowb + (size_t)(qs + r32) * dil + wres) * LDQ + C_BQ + hcol;
; #pragma unroll
;       for (int ks = 0; ks < 8; ++ks) Q[ks] = *(const bf16x8*)(qr + 16 * ks + 8 * hi); }
;     f32x16 O[4]; float l = 0.f;
; #pragma unroll
;     for (int db = 0; db < 4; ++db) zero16(O[db]);
;     constexpr int TK = SEG2 ? 32 : 64;
;     const int k_lo = SEG2 ? 0 : ((q0 - 64 > 0) ? q0 - 64 : 0), k_hi = SEG2 ? 128 : ((q0 + 320 < sub_len) ? q0 + 320 : sub_len);
;     const int nsteps = (k_hi - k_lo) / TK;
;     const int lrow = tid >> 3, lcb = (tid & 7) * 32;
;     const int lres = SEG2 ? res0 + (lrow >> 5) : res0, lkey = SEG2 ? (lrow & 31) : lrow;
;     const char* kg = (const char*)(R + (rowb + (size_t)(k_lo + lkey) * dil + lres) * LDQ + C_BK + hcol) + lcb;
;     const size_t sstep = (size_t)TK * dil * LDQ * 2;
;     constexpr int VOFF = (C_BV - C_BK) * 2, BUFB = 64 * KP + 64 * VP;
;     u32x4 kr0, kr1, vr0, vr1;
;     kr0 = *(const u32x4*)kg; kr1 = *(const u32x4*)(kg + 16); vr0 = *(const u32x4*)(kg + VOFF); vr1 = *(const u32x4*)(kg + VOFF + 16);
;     __syncthreads();
;     { LAS char* kw = lds + lrow * KP + lcb; LAS char* vw = lds + 64 * KP + lrow * VP + lcb;
;       *(LAS u32x4*)kw = kr0; *(LAS u32x4*)(kw + 16) = kr1; *(LAS u32x4*)vw = vr0; *(LAS u32x4*)(vw + 16) = vr1; }
;     __syncthreads();
;     const float qf = (float)(qs + r32 - 4 * hi);
.LBB0_319:
	s_mov_b64 s[60:61], -1
	s_and_b64 vcc, exec, s[4:5]
	s_cbranch_vccz .LBB0_310
	s_ashr_i32 s6, s85, 3
	s_mul_hi_i32 s4, s6, 0x2aaaaaab
	s_lshr_b32 s5, s4, 31
	s_ashr_i32 s4, s4, 1
	s_add_i32 s4, s4, s5
	s_mul_i32 s5, s4, 12
	s_sub_i32 s5, s6, s5
	s_and_b32 s84, s6, 3
	s_and_b32 s6, s5, -4
	s_or_b32 s6, s84, s6
	s_add_i32 s6, s6, 1
	v_cvt_f32_i32_e32 v16, s6
	v_mul_f32_e32 v16, 0xc1000000, v16
	v_div_scale_f32 v18, s[6:7], s93, s93, v16
	v_rcp_f32_e32 v19, v18
	v_div_scale_f32 v20, vcc, v16, s93, v16
	s_and_b32 s6, s85, 7
	v_fma_f32 v21, -v18, v19, 1.0
	v_fmac_f32_e32 v19, v21, v19
	v_mul_f32_e32 v21, v20, v19
	v_fma_f32 v22, -v18, v21, v20
	v_fmac_f32_e32 v21, v22, v19
	v_fma_f32 v18, -v18, v21, v20
	v_div_fmas_f32 v18, v18, v19, v21
	v_div_fixup_f32 v16, v18, s93, v16
	v_exp_f32_e32 v167, v16
	s_cmp_gt_u32 s5, 3
	s_cbranch_scc0 .LBB0_330
	s_ashr_i32 s62, s5, 2
	s_cmp_lg_u32 s62, 1
	s_cbranch_scc0 .LBB0_331
	s_mov_b32 s5, 0
	s_lshl_b32 s7, s6, 1
	v_mbcnt_lo_u32_b32 v16, -1, s5
	v_mbcnt_hi_u32_b32 v26, -1, v16
	v_add_u32_e32 v16, s80, v26
	s_lshl_b32 s5, s62, 9
	s_lshl_b32 s10, s84, 7
	v_ashrrev_i32_e32 v27, 3, v16
	v_lshlrev_b32_e32 v20, 5, v26
	v_ashrrev_i32_e32 v16, 8, v16
	s_or_b32 s26, s5, s10
	s_ashr_i32 s5, s4, 31
	s_waitcnt vmcnt(10)
	v_and_b32_e32 v146, 0xe0, v20
	v_add_u32_e32 v20, s7, v16
	s_add_i32 s10, s7, s39
	s_lshl_b64 s[66:67], s[4:5], 11
	v_lshlrev_b32_e32 v16, 4, v27
	v_ashrrev_i32_e32 v21, 31, v20
	s_add_u32 s64, s66, s10
	v_and_b32_e32 v22, 0x1f0, v16
	v_mov_b32_e32 v23, v17
	v_lshl_add_u64 v[20:21], s[66:67], 0, v[20:21]
	s_addc_u32 s65, s67, 0
	v_mov_b64_e32 v[18:19], s[18:19]
	s_ashr_i32 s27, s26, 31
	v_lshl_add_u64 v[20:21], v[20:21], 0, v[22:23]
	s_lshl_b64 s[60:61], s[26:27], 1
	v_mad_u64_u32 v[22:23], s[26:27], v20, s94, v[18:19]
	v_mad_i32_i24 v23, v21, s94, v23
	v_lshl_add_u64 v[22:23], v[22:23], 0, s[60:61]
	v_mov_b32_e32 v147, v17
	v_lshl_add_u64 v[22:23], v[22:23], 0, v[146:147]
	v_lshl_add_u64 v[24:25], v[22:23], 0, s[48:49]
	v_add_co_u32_e32 v22, vcc, s95, v22
	s_waitcnt vmcnt(9)
	v_mul_lo_u32 v152, v27, s96
	v_addc_co_u32_e32 v23, vcc, 0, v23, vcc
	global_load_dwordx4 v[98:101], v[22:23], off offset:2048
	global_load_dwordx4 v[102:105], v[24:25], off offset:16
	global_load_dwordx4 v[118:121], v[24:25], off offset:3072
	global_load_dwordx4 v[122:125], v[24:25], off offset:3088
	v_and_b32_e32 v24, 31, v26
	v_or_b32_e32 v16, s87, v24
	v_lshlrev_b32_e32 v16, 4, v16
	v_lshl_add_u64 v[22:23], s[64:65], 0, v[16:17]
	v_mad_u64_u32 v[18:19], s[26:27], v22, s94, v[18:19]
	v_bfe_u32 v25, v26, 5, 1
	v_mad_i32_i24 v19, v23, s94, v19
	v_lshl_add_u64 v[18:19], v[18:19], 0, s[60:61]
	v_lshlrev_b32_e32 v16, 4, v25
	v_lshl_add_u64 v[18:19], v[18:19], 0, v[16:17]
	global_load_dwordx4 v[106:109], v[18:19], off offset:3072
	global_load_dwordx4 v[110:113], v[18:19], off offset:3104
	global_load_dwordx4 v[114:117], v[18:19], off offset:3136
	global_load_dwordx4 v[126:129], v[18:19], off offset:3168
	global_load_dwordx4 v[130:133], v[18:19], off offset:3200
	global_load_dwordx4 v[134:137], v[18:19], off offset:3232
	global_load_dwordx4 v[138:141], v[18:19], off offset:3264
	global_load_dwordx4 v[142:145], v[18:19], off offset:3296
	v_mul_f32_e32 v18, 0xc1800000, v167
	v_mul_f32_e32 v147, 0x3fb8aa3b, v18
	v_bfe_u32 v18, v26, 2, 2
	v_lshrrev_b32_e32 v22, 3, v26
	v_and_b32_e32 v19, 16, v26
	v_lshlrev_b32_e32 v23, 2, v26
	v_and_or_b32 v18, v22, 4, v18
	v_and_or_b32 v19, v23, 12, v19
	v_lshlrev_b32_e32 v22, 2, v25
	v_add_u32_e32 v23, s87, v24
	v_mul_u32_u24_e32 v154, 0x140, v18
	v_add3_u32 v18, 0, v152, v146
	v_mul_u32_u24_e32 v151, 0x110, v24
	s_waitcnt vmcnt(20)
	v_sub_u32_e32 v156, v23, v22
	v_mad_u64_u32 v[22:23], s[26:27], v27, 48, v[18:19]
	v_mad_u64_u32 v[24:25], s[26:27], v20, s94, 0
	v_readlane_b32 s7, v255, 12
	s_add_u32 s26, s7, s60
	v_mad_i32_i24 v21, v21, s94, v25
	v_or_b32_e32 v20, v24, v146
	s_addc_u32 s27, s92, s61
	v_mov_b32_e32 v32, v17
	v_mov_b32_e32 v33, v17
	v_mul_lo_u32 v153, v27, s97
	v_lshlrev_b32_e32 v155, 1, v19
	s_barrier
	v_lshl_add_u64 v[148:149], s[26:27], 0, v[20:21]
	v_mov_b32_e32 v19, v17
	v_mov_b32_e32 v20, v17
	v_mov_b32_e32 v21, v17
	v_mov_b32_e32 v23, v17
	v_mov_b32_e32 v24, v17
	v_mov_b32_e32 v25, v17
	v_mov_b32_e32 v26, v17
	v_mov_b32_e32 v27, v17
	v_mov_b32_e32 v28, v17
	v_mov_b32_e32 v29, v17
	v_mov_b32_e32 v30, v17
	s_waitcnt vmcnt(11)
	ds_write_b128 v18, v[98:101]
	s_waitcnt vmcnt(10)
	ds_write_b128 v18, v[102:105] offset:16
	s_waitcnt vmcnt(9)
	ds_write_b128 v22, v[118:121] offset:17408
	s_waitcnt vmcnt(8)
	ds_write_b128 v22, v[122:125] offset:17424
	v_mov_b32_e32 v18, v17
	v_mov_b32_e32 v22, v17
	v_mov_b32_e32 v31, v17
	v_mov_b64_e32 v[48:49], v[32:33]
	v_mov_b64_e32 v[64:65], v[32:33]
	v_mov_b64_e32 v[80:81], v[32:33]
	s_mov_b32 s5, 0
	v_mov_b32_e32 v157, 0
	v_mov_b64_e32 v[46:47], v[30:31]
	v_mov_b64_e32 v[44:45], v[28:29]
	v_mov_b64_e32 v[42:43], v[26:27]
	v_mov_b64_e32 v[40:41], v[24:25]
	v_mov_b64_e32 v[38:39], v[22:23]
	v_mov_b64_e32 v[36:37], v[20:21]
	v_mov_b64_e32 v[34:35], v[18:19]
	v_mov_b64_e32 v[62:63], v[30:31]
	v_mov_b64_e32 v[60:61], v[28:29]
	v_mov_b64_e32 v[58:59], v[26:27]
	v_mov_b64_e32 v[56:57], v[24:25]
	v_mov_b64_e32 v[54:55], v[22:23]
	v_mov_b64_e32 v[52:53], v[20:21]
	v_mov_b64_e32 v[50:51], v[18:19]
	v_mov_b64_e32 v[78:79], v[30:31]
	v_mov_b64_e32 v[76:77], v[28:29]
	v_mov_b64_e32 v[74:75], v[26:27]
	v_mov_b64_e32 v[72:73], v[24:25]
	v_mov_b64_e32 v[70:71], v[22:23]
	v_mov_b64_e32 v[68:69], v[20:21]
	v_mov_b64_e32 v[66:67], v[18:19]
	s_mov_b32 s7, 0
	s_waitcnt vmcnt(0) lgkmcnt(0)
	s_barrier
	s_branch .LBB0_324

; __device__ __forceinline__ unsigned cvtpk(float lo, float hi) { f32x2_t v = {lo, hi}; bf16x2_t b = __builtin_convertvector(v, bf16x2_t); return __builtin_bit_cast(unsigned, b); }
; template <int MODE>
; __device__ __forceinline__ void soft32(const f32x16& S, bf16x8 (&P)[2], float& l, float dbase, float nslope) {
;     float p[16];
; #pragma unroll
;     for (int r = 0; r < 16; ++r) {
;         float s = S[r];
;         if (MODE >= 1) { const float a = fabsf(dbase - (float)((r & 3) + 8 * (r >> 2))); s = fmaf(nslope, a, s); float e = __builtin_amdgcn_exp2f(s); if (MODE == 2) e = (a <= 64.f) ? e : 0.f; p[r] = e; }
;         else p[r] = __builtin_amdgcn_exp2f(s);
;         l += p[r];
;     }
; #pragma unroll
;     for (int s = 0; s < 2; ++s) { u32x4 w; w.x = cvtpk(p[8 * s + 0], p[8 * s + 1]); w.y = cvtpk(p[8 * s + 2], p[8 * s + 3]); w.z = cvtpk(p[8 * s + 4], p[8 * s + 5]); w.w = cvtpk(p[8 * s + 6], p[8 * s + 7]); P[s] = __builtin_bit_cast(bf16x8, w); }
; template <bool SEG2>
; __device__ __forceinline__ void attn_b_block_unit(LAS char* lds, bf16* R, float* LB, int b, int g, int j, int res0, int q0, int dil, float nslope, float negM0, int wave_id) {
;     ...
;         for (int hh = 0; hh < (SEG2 ? 1 : 2); ++hh) {
;             const int row0 = SEG2 ? 32 * (wave_id >> 2) : 32 * hh, kbase = SEG2 ? kb : kb + 32 * hh;
;             if (kbase + 31 >= qs - 64 && kbase <= qs + 95) {
;                 f32x16 S;
; #pragma unroll
;                 for (int r = 0; r < 16; ++r) S[r] = negM0;
;                 qk32<8>(S, Kb + row0 * KP, Q, 0, r32, hi);
;                 bf16x8 P[2];
;                 soft32<2>(S, P, l, qf - (float)kbase, nslope);
;                 pv32(O, P, Vb + row0 * VP, lane);
;             }
.LBB0_326:
	s_add_i32 s10, s5, 31
	s_cmp_lt_i32 s10, s88
	s_cselect_b64 s[26:27], -1, 0
	s_cmp_gt_u32 s5, s89
	s_cselect_b64 s[68:69], -1, 0
	s_or_b64 s[26:27], s[26:27], s[68:69]
	s_and_b64 vcc, exec, s[26:27]
	s_cbranch_vccnz .LBB0_328
	s_bitcmp1_b32 s7, 0
	s_cselect_b32 s10, 0x9400, 0
	s_add_i32 s10, s10, 0
	s_mul_i32 s26, s39, 0x2200
	s_add_i32 s26, s10, s26
	v_add3_u32 v170, s26, v151, v16
	ds_read_b128 v[158:161], v170
	ds_read_b128 v[162:165], v170 offset:32
	v_cvt_f32_i32_e32 v150, v156
	s_mul_i32 s26, s39, 0x2800
	s_waitcnt lgkmcnt(1)
	v_mfma_f32_32x32x16_bf16 v[82:97], v[158:161], v[106:109], v[0:15]
	v_add_f32_e32 v181, -1.0, v150
	v_add_f32_e64 v168, v150, s50
	v_add_f32_e64 v169, v150, s51
	v_cmp_le_f32_e64 vcc, |v150|, s33
	v_add_f32_e64 v172, v150, s52
	v_add_f32_e64 v173, v150, s53
	v_pk_add_f32 v[174:175], v[150:151], s[46:47] op_sel_hi:[0,1]
	v_pk_add_f32 v[176:177], v[150:151], s[54:55] op_sel_hi:[0,1]
	s_add_i32 s10, s10, s26
	s_waitcnt lgkmcnt(0)
	v_mfma_f32_32x32x16_bf16 v[82:97], v[162:165], v[110:113], v[82:97]
	ds_read_b128 v[158:161], v170 offset:64
	ds_read_b128 v[162:165], v170 offset:96
	v_add3_u32 v180, s10, v154, v155
	v_add_f32_e64 v178, v150, s56
	v_add_f32_e64 v179, v150, s57
	s_waitcnt lgkmcnt(1)
	v_mfma_f32_32x32x16_bf16 v[82:97], v[158:161], v[114:117], v[82:97]
	s_waitcnt lgkmcnt(0)
	v_mfma_f32_32x32x16_bf16 v[82:97], v[162:165], v[126:129], v[82:97]
	ds_read_b128 v[158:161], v170 offset:128
	ds_read_b128 v[162:165], v170 offset:160
	s_waitcnt lgkmcnt(1)
	v_mfma_f32_32x32x16_bf16 v[82:97], v[158:161], v[130:133], v[82:97]
	ds_read_b128 v[158:161], v170 offset:192
	s_waitcnt lgkmcnt(1)
	v_mfma_f32_32x32x16_bf16 v[82:97], v[162:165], v[134:137], v[82:97]
	ds_read_b128 v[162:165], v170 offset:224
	v_add_f32_e64 v170, v150, s44
	v_add_f32_e64 v171, v150, s45
	s_waitcnt lgkmcnt(1)
	v_mfma_f32_32x32x16_bf16 v[82:97], v[158:161], v[138:141], v[82:97]
	ds_read_b64_tr_b16 v[158:159], v180 offset:17408
	ds_read_b64_tr_b16 v[160:161], v180 offset:19968
	s_waitcnt lgkmcnt(2)
	v_mfma_f32_32x32x16_bf16 v[82:97], v[162:165], v[142:145], v[82:97]
	s_nop 11
	v_fma_f32 v82, v147, |v150|, v82
	v_fma_f32 v83, v147, |v181|, v83
	v_exp_f32_e32 v82, v82
	v_fma_f32 v85, v147, |v169|, v85
	v_exp_f32_e32 v83, v83
	v_fma_f32 v84, v147, |v168|, v84
	v_exp_f32_e32 v85, v85
	v_fma_f32 v87, v147, |v171|, v87
	v_exp_f32_e32 v84, v84
	v_fma_f32 v86, v147, |v170|, v86
	v_exp_f32_e32 v87, v87
	v_cndmask_b32_e32 v182, 0, v82, vcc
	v_cmp_le_f32_e64 vcc, |v181|, s33
	v_fma_f32 v89, v147, |v173|, v89
	v_exp_f32_e32 v86, v86
	v_cndmask_b32_e32 v181, 0, v83, vcc
	v_cmp_le_f32_e64 vcc, |v169|, s33
	v_fma_f32 v88, v147, |v172|, v88
	v_exp_f32_e32 v89, v89
	v_cndmask_b32_e32 v169, 0, v85, vcc
	v_cmp_le_f32_e64 vcc, |v168|, s33
	v_fma_f32 v91, v147, |v175|, v91
	v_exp_f32_e32 v88, v88
	v_cndmask_b32_e32 v168, 0, v84, vcc
	v_cmp_le_f32_e64 vcc, |v171|, s33
	v_fma_f32 v90, v147, |v174|, v90
	v_exp_f32_e32 v91, v91
	v_cndmask_b32_e32 v171, 0, v87, vcc
	v_cmp_le_f32_e64 vcc, |v170|, s33
	v_fma_f32 v93, v147, |v177|, v93
	v_exp_f32_e32 v90, v90
	v_cndmask_b32_e32 v170, 0, v86, vcc
	v_cmp_le_f32_e64 vcc, |v173|, s33
	v_fma_f32 v92, v147, |v176|, v92
	v_exp_f32_e32 v93, v93
	v_cndmask_b32_e32 v173, 0, v89, vcc
	v_cmp_le_f32_e64 vcc, |v172|, s33
	v_exp_f32_e32 v92, v92
	v_fma_f32 v95, v147, |v179|, v95
	v_cndmask_b32_e32 v172, 0, v88, vcc
	v_cmp_le_f32_e64 vcc, |v175|, s33
	v_cvt_pk_bf16_f32 v82, v182, v181
	v_cvt_pk_bf16_f32 v83, v168, v169
	v_cndmask_b32_e32 v175, 0, v91, vcc
	v_cmp_le_f32_e64 vcc, |v174|, s33
	v_cvt_pk_bf16_f32 v84, v170, v171
	v_cvt_pk_bf16_f32 v85, v172, v173
	v_cndmask_b32_e32 v174, 0, v90, vcc
	v_cmp_le_f32_e64 vcc, |v177|, s33
	v_exp_f32_e32 v95, v95
	v_fma_f32 v94, v147, |v178|, v94
	v_cndmask_b32_e32 v177, 0, v93, vcc
	v_cmp_le_f32_e64 vcc, |v176|, s33
	s_waitcnt lgkmcnt(0)
	v_mfma_f32_32x32x16_bf16 v[66:81], v[158:161], v[82:85], v[66:81]
	v_exp_f32_e32 v94, v94
	v_cndmask_b32_e32 v176, 0, v92, vcc
	ds_read_b64_tr_b16 v[86:87], v180 offset:17472
	ds_read_b64_tr_b16 v[90:91], v180 offset:17536
	ds_read_b64_tr_b16 v[162:163], v180 offset:17600
	ds_read_b64_tr_b16 v[88:89], v180 offset:20032
	ds_read_b64_tr_b16 v[92:93], v180 offset:20096
	ds_read_b64_tr_b16 v[164:165], v180 offset:20160
	v_cmp_le_f32_e64 vcc, |v179|, s33
	s_nop 1
	v_cndmask_b32_e32 v179, 0, v95, vcc
	s_waitcnt lgkmcnt(2)
	v_mfma_f32_32x32x16_bf16 v[50:65], v[86:89], v[82:85], v[50:65]
	v_add_f32_e64 v86, v150, s58
	v_add_f32_e64 v87, v150, s59
	v_fma_f32 v88, v147, |v87|, v97
	v_exp_f32_e32 v88, v88
	v_fma_f32 v89, v147, |v86|, v96
	v_exp_f32_e32 v89, v89
	v_cmp_le_f32_e64 vcc, |v178|, s33
	s_waitcnt lgkmcnt(1)
	v_mfma_f32_32x32x16_bf16 v[34:49], v[90:93], v[82:85], v[34:49]
	ds_read_b64_tr_b16 v[90:91], v180 offset:22528
	ds_read_b64_tr_b16 v[92:93], v180 offset:25088
	v_cndmask_b32_e32 v178, 0, v94, vcc
	v_cmp_le_f32_e64 vcc, |v87|, s33
	v_cvt_pk_bf16_f32 v87, v176, v177
	s_nop 0
	v_cndmask_b32_e32 v150, 0, v88, vcc
	v_cmp_le_f32_e64 vcc, |v86|, s33
	v_cvt_pk_bf16_f32 v86, v174, v175
	v_cvt_pk_bf16_f32 v88, v178, v179
	v_cndmask_b32_e32 v183, 0, v89, vcc
	s_waitcnt lgkmcnt(2)
	v_mfma_f32_32x32x16_bf16 v[18:33], v[162:165], v[82:85], v[18:33]
	v_cvt_pk_bf16_f32 v89, v183, v150
	ds_read_b64_tr_b16 v[82:83], v180 offset:22592
	ds_read_b64_tr_b16 v[94:95], v180 offset:22656
	ds_read_b64_tr_b16 v[158:159], v180 offset:22720
	ds_read_b64_tr_b16 v[84:85], v180 offset:25152
	ds_read_b64_tr_b16 v[96:97], v180 offset:25216
	ds_read_b64_tr_b16 v[160:161], v180 offset:25280
	s_waitcnt lgkmcnt(6)
	v_mfma_f32_32x32x16_bf16 v[66:81], v[90:93], v[86:89], v[66:81]
	v_add_f32_e32 v90, v157, v182
	v_add_f32_e32 v90, v181, v90
	s_waitcnt lgkmcnt(2)
	v_mfma_f32_32x32x16_bf16 v[50:65], v[82:85], v[86:89], v[50:65]
	v_add_f32_e32 v82, v168, v90
	v_add_f32_e32 v82, v169, v82
	v_add_f32_e32 v82, v170, v82
	v_add_f32_e32 v82, v171, v82
	v_add_f32_e32 v82, v172, v82
	v_add_f32_e32 v82, v173, v82
	v_add_f32_e32 v82, v174, v82
	s_waitcnt lgkmcnt(1)
	v_mfma_f32_32x32x16_bf16 v[34:49], v[94:97], v[86:89], v[34:49]
	v_add_f32_e32 v82, v175, v82
	v_add_f32_e32 v82, v176, v82
	v_add_f32_e32 v82, v177, v82
	v_add_f32_e32 v82, v178, v82
	v_add_f32_e32 v82, v179, v82
	v_add_f32_e32 v82, v183, v82
	v_add_f32_e32 v157, v150, v82
	s_waitcnt lgkmcnt(0)
	v_mfma_f32_32x32x16_bf16 v[18:33], v[158:161], v[86:89], v[18:33]

; __device__ __forceinline__ int tid_fresh(int wave) { return wave * 64 + lane_id_fresh(); }
; #define LAS __attribute__((address_space(3)))
; template <bool SEG2>
; __device__ __forceinline__ void attn_b_block_unit(LAS char* lds, bf16* R, float* LB, int b, int g, int j, int res0, int q0, int dil, float nslope, float negM0, int wave_id) {
;     const int tid = pg8::tid_fresh(wave_id), lane = tid & 63, r32 = lane & 31, hi = lane >> 5;
;     const int sub_len = SEQ / dil, hcol = (g * 4 + j) * 128;
;     const int wres = SEG2 ? res0 + (wave_id >> 2) : res0;
;     const int qs = SEG2 ? 32 * (wave_id & 3) : q0 + 32 * wave_id;
;     const size_t rowb = (size_t)b * SEQ;
;     bf16x8 Q[8];
;     { const bf16* qr = R + (rowb + (size_t)(qs + r32) * dil + wres) * LDQ + C_BQ + hcol;
; #pragma unroll
;       for (int ks = 0; ks < 8; ++ks) Q[ks] = *(const bf16x8*)(qr + 16 * ks + 8 * hi); }
;     f32x16 O[4]; float l = 0.f;
; #pragma unroll
;     for (int db = 0; db < 4; ++db) zero16(O[db]);
;     constexpr int TK = SEG2 ? 32 : 64;
;     const int k_lo = SEG2 ? 0 : ((q0 - 64 > 0) ? q0 - 64 : 0), k_hi = SEG2 ? 128 : ((q0 + 320 < sub_len) ? q0 + 320 : sub_len);
;     const int nsteps = (k_hi - k_lo) / TK;
;     const int lrow = tid >> 3, lcb = (tid & 7) * 32;
;     const int lres = SEG2 ? res0 + (lrow >> 5) : res0, lkey = SEG2 ? (lrow & 31) : lrow;
;     const char* kg = (const char*)(R + (rowb + (size_t)(k_lo + lkey) * dil + lres) * LDQ + C_BK + hcol) + lcb;
;     const size_t sstep = (size_t)TK * dil * LDQ * 2;
;     constexpr int VOFF = (C_BV - C_BK) * 2, BUFB = 64 * KP + 64 * VP;
;     u32x4 kr0, kr1, vr0, vr1;
;     kr0 = *(const u32x4*)kg; kr1 = *(const u32x4*)(kg + 16); vr0 = *(const u32x4*)(kg + VOFF); vr1 = *(const u32x4*)(kg + VOFF + 16);
;     __syncthreads();
;     { LAS char* kw = lds + lrow * KP + lcb; LAS char* vw = lds + 64 * KP + lrow * VP + lcb;
;       *(LAS u32x4*)kw = kr0; *(LAS u32x4*)(kw + 16) = kr1; *(LAS u32x4*)vw = vr0; *(LAS u32x4*)(vw + 16) = vr1; }
;     __syncthreads();
;     const float qf = (float)(qs + r32 - 4 * hi);
.LBB0_350:
	s_mov_b32 s5, 0
	s_lshl_b32 s7, s6, 8
	v_mbcnt_lo_u32_b32 v16, -1, s5
	v_mbcnt_hi_u32_b32 v22, -1, v16
	v_and_b32_e32 v23, 31, v22
	s_add_i32 s6, s7, s86
	s_ashr_i32 s5, s4, 31
	s_lshl_b64 s[62:63], s[4:5], 11
	v_or_b32_e32 v18, s6, v23
	v_mov_b32_e32 v19, v17
	v_lshl_add_u64 v[20:21], s[62:63], 0, v[18:19]
	v_mov_b64_e32 v[26:27], s[18:19]
	v_mad_u64_u32 v[28:29], s[26:27], v20, s94, v[26:27]
	v_bfe_u32 v24, v22, 5, 1
	v_mad_i32_i24 v29, v21, s94, v29
	s_lshl_b32 s10, s84, 8
	v_add_u32_e32 v16, s80, v22
	v_lshl_add_u64 v[20:21], v[28:29], 0, s[10:11]
	s_waitcnt vmcnt(10)
	v_lshlrev_b32_e32 v146, 4, v24
	v_mov_b32_e32 v147, v17
	v_sub_u32_e64 v25, s7, 64 clamp
	v_ashrrev_i32_e32 v19, 3, v16
	v_lshl_add_u64 v[28:29], v[20:21], 0, v[146:147]
	v_add_u32_e32 v20, v19, v25
	v_ashrrev_i32_e32 v21, 31, v20
	v_lshl_add_u64 v[30:31], s[62:63], 0, v[20:21]
	global_load_dwordx4 v[98:101], v[28:29], off offset:3072
	global_load_dwordx4 v[102:105], v[28:29], off offset:3104
	global_load_dwordx4 v[106:109], v[28:29], off offset:3136
	global_load_dwordx4 v[110:113], v[28:29], off offset:3168
	v_mad_u64_u32 v[26:27], s[26:27], v30, s94, v[26:27]
	v_lshlrev_b32_e32 v16, 5, v22
	v_mad_i32_i24 v27, v31, s94, v27
	v_and_b32_e32 v16, 0xe0, v16
	v_lshl_add_u64 v[26:27], v[26:27], 0, s[10:11]
	v_lshl_add_u64 v[26:27], v[26:27], 0, v[16:17]
	v_lshl_add_u64 v[30:31], v[26:27], 0, s[48:49]
	v_add_co_u32_e32 v26, vcc, s95, v26
	s_min_u32 s5, s7, 0x6c0
	s_nop 0
	v_addc_co_u32_e32 v27, vcc, 0, v27, vcc
	global_load_dwordx4 v[114:117], v[26:27], off offset:2048
	global_load_dwordx4 v[118:121], v[30:31], off offset:16
	global_load_dwordx4 v[138:141], v[30:31], off offset:3072
	global_load_dwordx4 v[142:145], v[30:31], off offset:3088
	global_load_dwordx4 v[122:125], v[28:29], off offset:3200
	global_load_dwordx4 v[126:129], v[28:29], off offset:3232
	global_load_dwordx4 v[130:133], v[28:29], off offset:3264
	global_load_dwordx4 v[134:137], v[28:29], off offset:3296
	v_readfirstlane_b32 s10, v25
	s_sub_i32 s5, s5, s10
	s_addk_i32 s5, 0x140
	v_mul_lo_u32 v147, v19, s96
	v_readfirstlane_b32 s7, v25
	s_cmp_lt_i32 s5, 64
	v_add3_u32 v26, 0, v147, v16
	v_mad_u64_u32 v[28:29], s[26:27], v19, 48, v[26:27]
	s_barrier
	s_waitcnt vmcnt(7)
	ds_write_b128 v26, v[114:117]
	s_waitcnt vmcnt(6)
	ds_write_b128 v26, v[118:121] offset:16
	s_waitcnt vmcnt(5)
	ds_write_b128 v28, v[138:141] offset:17408
	s_waitcnt vmcnt(4)
	ds_write_b128 v28, v[142:145] offset:17424
	s_waitcnt vmcnt(0) lgkmcnt(0)
	s_barrier
	s_cbranch_scc1 .LBB0_362
	v_mul_lo_u32 v151, v19, s97
	v_lshlrev_b32_e32 v19, 2, v24
	v_sub_u32_e32 v18, v18, v19
	v_and_b32_e32 v21, 63, v22
	v_cvt_f32_i32_e32 v152, v18
	v_bfe_u32 v18, v22, 2, 2
	v_and_b32_e32 v19, 16, v22
	v_lshrrev_b32_e32 v22, 3, v22
	v_and_or_b32 v18, v22, 4, v18
	v_mul_u32_u24_e32 v154, 0x140, v18
	v_lshlrev_b32_e32 v18, 2, v21
	v_and_or_b32 v18, v18, 12, v19
	v_lshlrev_b32_e32 v155, 1, v18
	v_mad_i64_i32 v[18:19], s[26:27], v20, s94, 0
	s_ashr_i32 s10, s5, 6
	v_mad_i64_i32 v[18:19], s[4:5], s4, v166, v[18:19]
	s_lshl_b32 s4, s85, 5
	s_and_b32 s4, s4, 0x300
	v_or_b32_e32 v18, s4, v18
	v_or_b32_e32 v18, v18, v16
	v_mov_b32_e32 v32, v17
	v_mov_b32_e32 v33, v17
	v_mul_u32_u24_e32 v153, 0x110, v23
	v_lshl_add_u64 v[148:149], s[22:23], 0, v[18:19]
	v_mov_b32_e32 v18, v17
	v_mov_b32_e32 v19, v17
	v_mov_b32_e32 v20, v17
	v_mov_b32_e32 v21, v17
	v_mov_b32_e32 v22, v17
	v_mov_b32_e32 v23, v17
	v_mov_b32_e32 v24, v17
	v_mov_b32_e32 v25, v17
	v_mov_b32_e32 v26, v17
	v_mov_b32_e32 v27, v17
	v_mov_b32_e32 v28, v17
	v_mov_b32_e32 v29, v17
	v_mov_b32_e32 v30, v17
	v_mov_b32_e32 v31, v17
	v_mov_b64_e32 v[48:49], v[32:33]
	v_mov_b64_e32 v[64:65], v[32:33]
	v_mov_b64_e32 v[80:81], v[32:33]
	v_mul_f32_e32 v150, 0xbfb8aa3b, v167
	s_sub_i32 s66, s6, 64
	s_add_i32 s67, s6, 0x5f
	s_mov_b32 s4, 0
	v_mov_b32_e32 v156, 0
	v_mov_b64_e32 v[46:47], v[30:31]
	v_mov_b64_e32 v[44:45], v[28:29]
	v_mov_b64_e32 v[42:43], v[26:27]
	v_mov_b64_e32 v[40:41], v[24:25]
	v_mov_b64_e32 v[38:39], v[22:23]
	v_mov_b64_e32 v[36:37], v[20:21]
	v_mov_b64_e32 v[34:35], v[18:19]
	v_mov_b64_e32 v[62:63], v[30:31]
	v_mov_b64_e32 v[60:61], v[28:29]
	v_mov_b64_e32 v[58:59], v[26:27]
	v_mov_b64_e32 v[56:57], v[24:25]
	v_mov_b64_e32 v[54:55], v[22:23]
	v_mov_b64_e32 v[52:53], v[20:21]
	v_mov_b64_e32 v[50:51], v[18:19]
	v_mov_b64_e32 v[78:79], v[30:31]
	v_mov_b64_e32 v[76:77], v[28:29]
	v_mov_b64_e32 v[74:75], v[26:27]
	v_mov_b64_e32 v[72:73], v[24:25]
	v_mov_b64_e32 v[70:71], v[22:23]
	v_mov_b64_e32 v[68:69], v[20:21]
	v_mov_b64_e32 v[66:67], v[18:19]

; #define LAS __attribute__((address_space(3)))
; __device__ __forceinline__ s16x4 vtr(const LAS char* p) { return __builtin_bit_cast(s16x4, __builtin_amdgcn_ds_read_tr16_b64_v4i16((LAS v4i16_t*)p)); }
; template <int NK>
; __device__ __forceinline__ void qk32(f32x16& S, const LAS char* Kp, const bf16x8* Q, int ks0, int r32, int hi) {
;     const LAS char* kb = Kp + r32 * KP + hi * 16 + ks0 * 32;
; #pragma unroll
;     for (int ks = 0; ks < NK; ++ks) { const bf16x8 kf = *(const LAS bf16x8*)(kb + ks * 32); S = __builtin_amdgcn_mfma_f32_32x32x16_bf16(kf, Q[ks0 + ks], S, 0, 0, 0); }
; }
; __device__ __forceinline__ void pv32(f32x16 (&O)[4], const bf16x8 (&P)[2], const LAS char* Vp, int lane) {
;     const int i = lane & 15, q = i >> 2, p = i & 3, dsel = (lane >> 4) & 1, h = lane >> 5;
;     const LAS char* vb = Vp + (4 * h + q) * VP + (16 * dsel + 4 * p) * 2;
; #pragma unroll
;     for (int s = 0; s < 2; ++s)
; #pragma unroll
;         for (int db = 0; db < 4; ++db) {
;             const s16x4 lo = vtr(vb + (16 * s) * VP + db * 64), hi4 = vtr(vb + (16 * s + 8) * VP + db * 64);
;             const bf16x8 a = (bf16x8){lo[0], lo[1], lo[2], lo[3], hi4[0], hi4[1], hi4[2], hi4[3]};
;             O[db] = __builtin_amdgcn_mfma_f32_32x32x16_bf16(a, P[s], O[db], 0, 0, 0);
;         }
; template <bool SEG2>
; __device__ __forceinline__ void attn_b_block_unit(LAS char* lds, bf16* R, float* LB, int b, int g, int j, int res0, int q0, int dil, float nslope, float negM0, int wave_id) {
;     ...
;         for (int hh = 0; hh < (SEG2 ? 1 : 2); ++hh) {
;             const int row0 = SEG2 ? 32 * (wave_id >> 2) : 32 * hh, kbase = SEG2 ? kb : kb + 32 * hh;
;             if (kbase + 31 >= qs - 64 && kbase <= qs + 95) {
;                 f32x16 S;
; #pragma unroll
;                 for (int r = 0; r < 16; ++r) S[r] = negM0;
;                 qk32<8>(S, Kb + row0 * KP, Q, 0, r32, hi);
;                 bf16x8 P[2];
;                 soft32<2>(S, P, l, qf - (float)kbase, nslope);
;                 pv32(O, P, Vb + row0 * VP, lane);
;             }
.LBB0_354:
	s_bitcmp1_b32 s4, 0
	s_cselect_b32 s4, 0x9400, 0
	s_add_i32 s4, s4, 0
	v_add_u32_e32 v82, s4, v153
	v_add_u32_e32 v83, s4, v154
	s_add_i32 s4, s7, 31
	s_cmp_lt_i32 s4, s66
	s_cselect_b64 s[4:5], -1, 0
	s_cmp_gt_u32 s7, s67
	s_cselect_b64 s[26:27], -1, 0
	s_or_b64 s[4:5], s[4:5], s[26:27]
	s_and_b64 vcc, exec, s[4:5]
	v_add_u32_e32 v158, v82, v146
	v_add_u32_e32 v157, v83, v155
	s_cbranch_vccnz .LBB0_356
	ds_read_b128 v[160:163], v158
	ds_read_b128 v[168:171], v158 offset:32
	v_cvt_f32_u32_e32 v159, s7
	s_waitcnt lgkmcnt(1)
	v_mfma_f32_32x32x16_bf16 v[82:97], v[160:163], v[98:101], v[0:15]
	ds_read_b128 v[160:163], v158 offset:64
	s_waitcnt lgkmcnt(1)
	v_mfma_f32_32x32x16_bf16 v[82:97], v[168:171], v[102:105], v[82:97]
	s_waitcnt lgkmcnt(0)
	v_mfma_f32_32x32x16_bf16 v[82:97], v[160:163], v[106:109], v[82:97]
	ds_read_b128 v[160:163], v158 offset:96
	s_waitcnt lgkmcnt(0)
	v_mfma_f32_32x32x16_bf16 v[82:97], v[160:163], v[110:113], v[82:97]
	ds_read_b128 v[160:163], v158 offset:128
	s_waitcnt lgkmcnt(0)
	v_mfma_f32_32x32x16_bf16 v[82:97], v[160:163], v[122:125], v[82:97]
	ds_read_b128 v[160:163], v158 offset:160
	s_waitcnt lgkmcnt(0)
	v_mfma_f32_32x32x16_bf16 v[82:97], v[160:163], v[126:129], v[82:97]
	ds_read_b128 v[160:163], v158 offset:192
	s_waitcnt lgkmcnt(0)
	v_mfma_f32_32x32x16_bf16 v[82:97], v[160:163], v[130:133], v[82:97]
	ds_read_b128 v[160:163], v158 offset:224
	s_waitcnt lgkmcnt(0)
	v_mfma_f32_32x32x16_bf16 v[82:97], v[160:163], v[134:137], v[82:97]
	v_sub_f32_e32 v160, v152, v159
	v_cmp_le_f32_e64 vcc, |v160|, s33
	s_nop 9
	v_fma_f32 v82, v150, |v160|, v82
	v_exp_f32_e32 v82, v82
	s_nop 0
	v_cndmask_b32_e32 v159, 0, v82, vcc
	v_add_f32_e32 v82, v156, v159
	v_add_f32_e32 v156, -1.0, v160
	v_fma_f32 v83, v150, |v156|, v83
	v_exp_f32_e32 v83, v83
	v_cmp_le_f32_e64 vcc, |v156|, s33
	s_nop 1
	v_cndmask_b32_e32 v161, 0, v83, vcc
	v_add_f32_e32 v156, v161, v82
	v_pk_add_f32 v[82:83], v[160:161], s[50:51] op_sel_hi:[0,1]
	v_fma_f32 v84, v150, |v82|, v84
	v_exp_f32_e32 v84, v84
	v_fma_f32 v85, v150, |v83|, v85
	v_exp_f32_e32 v85, v85
	v_cmp_le_f32_e64 vcc, |v82|, s33
	v_cmp_le_f32_e64 s[4:5], |v83|, s33
	s_nop 0
	v_cndmask_b32_e32 v84, 0, v84, vcc
	v_cndmask_b32_e64 v85, 0, v85, s[4:5]
	v_add_f32_e32 v82, v84, v156
	v_add_f32_e32 v156, v85, v82
	v_pk_add_f32 v[82:83], v[160:161], s[44:45] op_sel_hi:[0,1]
	v_fma_f32 v86, v150, |v82|, v86
	v_exp_f32_e32 v86, v86
	v_fma_f32 v87, v150, |v83|, v87
	v_exp_f32_e32 v87, v87
	v_cmp_le_f32_e64 vcc, |v82|, s33
	v_cmp_le_f32_e64 s[4:5], |v83|, s33
	s_nop 0
	v_cndmask_b32_e32 v163, 0, v86, vcc
	v_cndmask_b32_e64 v162, 0, v87, s[4:5]
	v_add_f32_e32 v82, v163, v156
	v_add_f32_e32 v86, v162, v82
	v_pk_add_f32 v[82:83], v[160:161], s[52:53] op_sel_hi:[0,1]
	v_fma_f32 v87, v150, |v82|, v88
	v_exp_f32_e32 v87, v87
	v_fma_f32 v88, v150, |v83|, v89
	v_exp_f32_e32 v88, v88
	v_cmp_le_f32_e64 vcc, |v82|, s33
	v_cmp_le_f32_e64 s[4:5], |v83|, s33
	s_nop 0
	v_cndmask_b32_e32 v164, 0, v87, vcc
	v_cndmask_b32_e64 v89, 0, v88, s[4:5]
	v_add_f32_e32 v82, v164, v86
	v_add_f32_e32 v86, v89, v82
	v_pk_add_f32 v[82:83], v[160:161], s[46:47] op_sel_hi:[0,1]
	v_fma_f32 v87, v150, |v82|, v90
	v_exp_f32_e32 v87, v87
	v_fma_f32 v88, v150, |v83|, v91
	v_exp_f32_e32 v88, v88
	v_cmp_le_f32_e64 vcc, |v82|, s33
	v_cmp_le_f32_e64 s[4:5], |v83|, s33
	v_cvt_pk_bf16_f32 v89, v164, v89
	v_cndmask_b32_e32 v91, 0, v87, vcc
	v_cndmask_b32_e64 v90, 0, v88, s[4:5]
	v_add_f32_e32 v82, v91, v86
	v_add_f32_e32 v86, v90, v82
	v_pk_add_f32 v[82:83], v[160:161], s[54:55] op_sel_hi:[0,1]
	v_fma_f32 v87, v150, |v82|, v92
	v_exp_f32_e32 v87, v87
	v_fma_f32 v88, v150, |v83|, v93
	v_exp_f32_e32 v88, v88
	v_cmp_le_f32_e64 vcc, |v82|, s33
	v_cmp_le_f32_e64 s[4:5], |v83|, s33
	s_nop 0
	v_cndmask_b32_e32 v93, 0, v87, vcc
	v_cndmask_b32_e64 v92, 0, v88, s[4:5]
	v_add_f32_e32 v82, v93, v86
	v_add_f32_e32 v86, v92, v82
	v_pk_add_f32 v[82:83], v[160:161], s[56:57] op_sel_hi:[0,1]
	v_fma_f32 v87, v150, |v82|, v94
	v_exp_f32_e32 v87, v87
	v_fma_f32 v88, v150, |v83|, v95
	v_exp_f32_e32 v88, v88
	v_cmp_le_f32_e64 vcc, |v82|, s33
	v_cmp_le_f32_e64 s[4:5], |v83|, s33
	s_nop 0
	v_cndmask_b32_e32 v95, 0, v87, vcc
	v_cndmask_b32_e64 v94, 0, v88, s[4:5]
	v_add_f32_e32 v82, v95, v86
	v_add_f32_e32 v86, v94, v82
	v_pk_add_f32 v[82:83], v[160:161], s[58:59] op_sel_hi:[0,1]
	v_fma_f32 v87, v150, |v82|, v96
	v_exp_f32_e32 v87, v87
	v_fma_f32 v88, v150, |v83|, v97
	v_exp_f32_e32 v88, v88
	v_cmp_le_f32_e64 vcc, |v82|, s33
	v_cmp_le_f32_e64 s[4:5], |v83|, s33
	v_cvt_pk_bf16_f32 v83, v93, v92
	v_cndmask_b32_e32 v97, 0, v87, vcc
	v_cndmask_b32_e64 v96, 0, v88, s[4:5]
	v_add_f32_e32 v82, v97, v86
	v_add_f32_e32 v156, v96, v82
	v_cvt_pk_bf16_f32 v82, v91, v90
	ds_read_b64_tr_b16 v[90:91], v157 offset:17408
	ds_read_b64_tr_b16 v[92:93], v157 offset:19968
	v_cvt_pk_bf16_f32 v86, v159, v161
	v_cvt_pk_bf16_f32 v87, v84, v85
	v_cvt_pk_bf16_f32 v88, v163, v162
	v_cvt_pk_bf16_f32 v84, v95, v94
	v_cvt_pk_bf16_f32 v85, v97, v96
	s_waitcnt lgkmcnt(0)
	v_mfma_f32_32x32x16_bf16 v[66:81], v[90:93], v[86:89], v[66:81]
	ds_read_b64_tr_b16 v[90:91], v157 offset:17472
	ds_read_b64_tr_b16 v[92:93], v157 offset:20032
	s_waitcnt lgkmcnt(0)
	v_mfma_f32_32x32x16_bf16 v[50:65], v[90:93], v[86:89], v[50:65]
	ds_read_b64_tr_b16 v[90:91], v157 offset:17536
	ds_read_b64_tr_b16 v[92:93], v157 offset:20096
	s_waitcnt lgkmcnt(0)
	v_mfma_f32_32x32x16_bf16 v[34:49], v[90:93], v[86:89], v[34:49]
	ds_read_b64_tr_b16 v[90:91], v157 offset:17600
	ds_read_b64_tr_b16 v[92:93], v157 offset:20160
	s_waitcnt lgkmcnt(0)
	v_mfma_f32_32x32x16_bf16 v[18:33], v[90:93], v[86:89], v[18:33]
	ds_read_b64_tr_b16 v[86:87], v157 offset:22528
	ds_read_b64_tr_b16 v[88:89], v157 offset:25088
	s_waitcnt lgkmcnt(0)
	v_mfma_f32_32x32x16_bf16 v[66:81], v[86:89], v[82:85], v[66:81]
	ds_read_b64_tr_b16 v[86:87], v157 offset:22592
	ds_read_b64_tr_b16 v[88:89], v157 offset:25152
	s_waitcnt lgkmcnt(0)
	v_mfma_f32_32x32x16_bf16 v[50:65], v[86:89], v[82:85], v[50:65]
	ds_read_b64_tr_b16 v[86:87], v157 offset:22656
	ds_read_b64_tr_b16 v[88:89], v157 offset:25216
	s_waitcnt lgkmcnt(0)
	v_mfma_f32_32x32x16_bf16 v[34:49], v[86:89], v[82:85], v[34:49]
	ds_read_b64_tr_b16 v[86:87], v157 offset:22720
	ds_read_b64_tr_b16 v[88:89], v157 offset:25280
	s_waitcnt lgkmcnt(0)
	v_mfma_f32_32x32x16_bf16 v[18:33], v[86:89], v[82:85], v[18:33]
; #define LAS __attribute__((address_space(3)))
; __device__ __forceinline__ s16x4 vtr(const LAS char* p) { return __builtin_bit_cast(s16x4, __builtin_amdgcn_ds_read_tr16_b64_v4i16((LAS v4i16_t*)p)); }
; template <int NK>
; __device__ __forceinline__ void qk32(f32x16& S, const LAS char* Kp, const bf16x8* Q, int ks0, int r32, int hi) {
;     const LAS char* kb = Kp + r32 * KP + hi * 16 + ks0 * 32;
; #pragma unroll
;     for (int ks = 0; ks < NK; ++ks) { const bf16x8 kf = *(const LAS bf16x8*)(kb + ks * 32); S = __builtin_amdgcn_mfma_f32_32x32x16_bf16(kf, Q[ks0 + ks], S, 0, 0, 0); }
; }
; __device__ __forceinline__ void pv32(f32x16 (&O)[4], const bf16x8 (&P)[2], const LAS char* Vp, int lane) {
;     const int i = lane & 15, q = i >> 2, p = i & 3, dsel = (lane >> 4) & 1, h = lane >> 5;
;     const LAS char* vb = Vp + (4 * h + q) * VP + (16 * dsel + 4 * p) * 2;
; #pragma unroll
;     for (int s = 0; s < 2; ++s)
; #pragma unroll
;         for (int db = 0; db < 4; ++db) {
;             const s16x4 lo = vtr(vb + (16 * s) * VP + db * 64), hi4 = vtr(vb + (16 * s + 8) * VP + db * 64);
;             const bf16x8 a = (bf16x8){lo[0], lo[1], lo[2], lo[3], hi4[0], hi4[1], hi4[2], hi4[3]};
;             O[db] = __builtin_amdgcn_mfma_f32_32x32x16_bf16(a, P[s], O[db], 0, 0, 0);
;         }
; template <bool SEG2>
; __device__ __forceinline__ void attn_b_block_unit(LAS char* lds, bf16* R, float* LB, int b, int g, int j, int res0, int q0, int dil, float nslope, float negM0, int wave_id) {
;     ...
;         for (int hh = 0; hh < (SEG2 ? 1 : 2); ++hh) {
;             const int row0 = SEG2 ? 32 * (wave_id >> 2) : 32 * hh, kbase = SEG2 ? kb : kb + 32 * hh;
;             if (kbase + 31 >= qs - 64 && kbase <= qs + 95) {
;                 f32x16 S;
; #pragma unroll
;                 for (int r = 0; r < 16; ++r) S[r] = negM0;
;                 qk32<8>(S, Kb + row0 * KP, Q, 0, r32, hi);
;                 bf16x8 P[2];
;                 soft32<2>(S, P, l, qf - (float)kbase, nslope);
;                 pv32(O, P, Vb + row0 * VP, lane);
;             }
.LBB0_356:
	s_add_i32 s4, s7, 32
	s_add_i32 s5, s7, 63
	s_cmp_lt_i32 s5, s66
	s_cselect_b64 s[26:27], -1, 0
	s_cmp_gt_u32 s4, s67
	s_cselect_b64 s[78:79], -1, 0
	s_or_b64 s[26:27], s[26:27], s[78:79]
	s_and_b64 vcc, exec, s[26:27]
	s_cbranch_vccnz .LBB0_358
	ds_read_b128 v[160:163], v158 offset:8704
	ds_read_b128 v[168:171], v158 offset:8736
	s_waitcnt lgkmcnt(1)
	v_mfma_f32_32x32x16_bf16 v[82:97], v[160:163], v[98:101], v[0:15]
	ds_read_b128 v[160:163], v158 offset:8768
	s_waitcnt lgkmcnt(1)
	v_mfma_f32_32x32x16_bf16 v[82:97], v[168:171], v[102:105], v[82:97]
	s_waitcnt lgkmcnt(0)
	v_mfma_f32_32x32x16_bf16 v[82:97], v[160:163], v[106:109], v[82:97]
	ds_read_b128 v[160:163], v158 offset:8800
	s_waitcnt lgkmcnt(0)
	v_mfma_f32_32x32x16_bf16 v[82:97], v[160:163], v[110:113], v[82:97]
	ds_read_b128 v[160:163], v158 offset:8832
	s_waitcnt lgkmcnt(0)
	v_mfma_f32_32x32x16_bf16 v[82:97], v[160:163], v[122:125], v[82:97]
	ds_read_b128 v[160:163], v158 offset:8864
	s_waitcnt lgkmcnt(0)
	v_mfma_f32_32x32x16_bf16 v[82:97], v[160:163], v[126:129], v[82:97]
	ds_read_b128 v[160:163], v158 offset:8896
	s_waitcnt lgkmcnt(0)
	v_mfma_f32_32x32x16_bf16 v[82:97], v[160:163], v[130:133], v[82:97]
	ds_read_b128 v[158:161], v158 offset:8928
	s_waitcnt lgkmcnt(0)
	v_mfma_f32_32x32x16_bf16 v[82:97], v[158:161], v[134:137], v[82:97]
	v_cvt_f32_u32_e32 v158, s4
	v_sub_f32_e32 v158, v152, v158
	v_cmp_le_f32_e64 vcc, |v158|, s33
	s_nop 8
	v_fma_f32 v82, v150, |v158|, v82
	v_exp_f32_e32 v82, v82
	s_nop 0
	v_cndmask_b32_e32 v159, 0, v82, vcc
	v_add_f32_e32 v82, v156, v159
	v_add_f32_e32 v156, -1.0, v158
	v_fma_f32 v83, v150, |v156|, v83
	v_exp_f32_e32 v83, v83
	v_cmp_le_f32_e64 vcc, |v156|, s33
	s_nop 1
	v_cndmask_b32_e32 v160, 0, v83, vcc
	v_add_f32_e32 v156, v160, v82
	v_pk_add_f32 v[82:83], v[158:159], s[50:51] op_sel_hi:[0,1]
	v_fma_f32 v84, v150, |v82|, v84
	v_exp_f32_e32 v84, v84
	v_fma_f32 v85, v150, |v83|, v85
	v_exp_f32_e32 v85, v85
	v_cmp_le_f32_e64 vcc, |v82|, s33
	v_cmp_le_f32_e64 s[4:5], |v83|, s33
	s_nop 0
	v_cndmask_b32_e32 v84, 0, v84, vcc
	v_cndmask_b32_e64 v85, 0, v85, s[4:5]
	v_add_f32_e32 v82, v84, v156
	v_add_f32_e32 v156, v85, v82
	v_pk_add_f32 v[82:83], v[158:159], s[44:45] op_sel_hi:[0,1]
	v_fma_f32 v86, v150, |v82|, v86
	v_exp_f32_e32 v86, v86
	v_fma_f32 v87, v150, |v83|, v87
	v_exp_f32_e32 v87, v87
	v_cmp_le_f32_e64 vcc, |v82|, s33
	v_cmp_le_f32_e64 s[4:5], |v83|, s33
	s_nop 0
	v_cndmask_b32_e32 v162, 0, v86, vcc
	v_cndmask_b32_e64 v161, 0, v87, s[4:5]
	v_add_f32_e32 v82, v162, v156
	v_add_f32_e32 v86, v161, v82
	v_pk_add_f32 v[82:83], v[158:159], s[52:53] op_sel_hi:[0,1]
	v_fma_f32 v87, v150, |v82|, v88
	v_exp_f32_e32 v87, v87
	v_fma_f32 v88, v150, |v83|, v89
	v_exp_f32_e32 v88, v88
	v_cmp_le_f32_e64 vcc, |v82|, s33
	v_cmp_le_f32_e64 s[4:5], |v83|, s33
	s_nop 0
	v_cndmask_b32_e32 v163, 0, v87, vcc
	v_cndmask_b32_e64 v89, 0, v88, s[4:5]
	v_add_f32_e32 v82, v163, v86
	v_add_f32_e32 v86, v89, v82
	v_pk_add_f32 v[82:83], v[158:159], s[46:47] op_sel_hi:[0,1]
	v_fma_f32 v87, v150, |v82|, v90
	v_exp_f32_e32 v87, v87
	v_fma_f32 v88, v150, |v83|, v91
	v_exp_f32_e32 v88, v88
	v_cmp_le_f32_e64 vcc, |v82|, s33
	v_cmp_le_f32_e64 s[4:5], |v83|, s33
	v_cvt_pk_bf16_f32 v89, v163, v89
	v_cndmask_b32_e32 v91, 0, v87, vcc
	v_cndmask_b32_e64 v90, 0, v88, s[4:5]
	v_add_f32_e32 v82, v91, v86
	v_add_f32_e32 v86, v90, v82
	v_pk_add_f32 v[82:83], v[158:159], s[54:55] op_sel_hi:[0,1]
	v_fma_f32 v87, v150, |v82|, v92
	v_exp_f32_e32 v87, v87
	v_fma_f32 v88, v150, |v83|, v93
	v_exp_f32_e32 v88, v88
	v_cmp_le_f32_e64 vcc, |v82|, s33
	v_cmp_le_f32_e64 s[4:5], |v83|, s33
	s_nop 0
	v_cndmask_b32_e32 v93, 0, v87, vcc
	v_cndmask_b32_e64 v92, 0, v88, s[4:5]
	v_add_f32_e32 v82, v93, v86
	v_add_f32_e32 v86, v92, v82
	v_pk_add_f32 v[82:83], v[158:159], s[56:57] op_sel_hi:[0,1]
	v_fma_f32 v87, v150, |v82|, v94
	v_exp_f32_e32 v87, v87
	v_fma_f32 v88, v150, |v83|, v95
	v_exp_f32_e32 v88, v88
	v_cmp_le_f32_e64 vcc, |v82|, s33
	v_cmp_le_f32_e64 s[4:5], |v83|, s33
	s_nop 0
	v_cndmask_b32_e32 v95, 0, v87, vcc
	v_cndmask_b32_e64 v94, 0, v88, s[4:5]
	v_add_f32_e32 v82, v95, v86
	v_add_f32_e32 v86, v94, v82
	v_pk_add_f32 v[82:83], v[158:159], s[58:59] op_sel_hi:[0,1]
	v_fma_f32 v87, v150, |v82|, v96
	v_exp_f32_e32 v87, v87
	v_fma_f32 v88, v150, |v83|, v97
	v_exp_f32_e32 v88, v88
	v_cmp_le_f32_e64 vcc, |v82|, s33
	v_cmp_le_f32_e64 s[4:5], |v83|, s33
	v_cvt_pk_bf16_f32 v83, v93, v92
	v_cndmask_b32_e32 v97, 0, v87, vcc
	v_cndmask_b32_e64 v96, 0, v88, s[4:5]
	v_add_f32_e32 v82, v97, v86
	v_add_f32_e32 v156, v96, v82
	v_cvt_pk_bf16_f32 v82, v91, v90
	ds_read_b64_tr_b16 v[90:91], v157 offset:27648
	ds_read_b64_tr_b16 v[92:93], v157 offset:30208
	v_cvt_pk_bf16_f32 v86, v159, v160
	v_cvt_pk_bf16_f32 v87, v84, v85
	v_cvt_pk_bf16_f32 v88, v162, v161
	v_cvt_pk_bf16_f32 v84, v95, v94
	v_cvt_pk_bf16_f32 v85, v97, v96
	s_waitcnt lgkmcnt(0)
	v_mfma_f32_32x32x16_bf16 v[66:81], v[90:93], v[86:89], v[66:81]
	ds_read_b64_tr_b16 v[90:91], v157 offset:27712
	ds_read_b64_tr_b16 v[92:93], v157 offset:30272
	s_waitcnt lgkmcnt(0)
	v_mfma_f32_32x32x16_bf16 v[50:65], v[90:93], v[86:89], v[50:65]
	ds_read_b64_tr_b16 v[90:91], v157 offset:27776
	ds_read_b64_tr_b16 v[92:93], v157 offset:30336
	s_waitcnt lgkmcnt(0)
	v_mfma_f32_32x32x16_bf16 v[34:49], v[90:93], v[86:89], v[34:49]
	ds_read_b64_tr_b16 v[90:91], v157 offset:27840
	ds_read_b64_tr_b16 v[92:93], v157 offset:30400
	s_waitcnt lgkmcnt(0)
	v_mfma_f32_32x32x16_bf16 v[18:33], v[90:93], v[86:89], v[18:33]
	ds_read_b64_tr_b16 v[86:87], v157 offset:32768
	ds_read_b64_tr_b16 v[88:89], v157 offset:35328
	s_waitcnt lgkmcnt(0)
	v_mfma_f32_32x32x16_bf16 v[66:81], v[86:89], v[82:85], v[66:81]
	ds_read_b64_tr_b16 v[86:87], v157 offset:32832
	ds_read_b64_tr_b16 v[88:89], v157 offset:35392
	s_waitcnt lgkmcnt(0)
	v_mfma_f32_32x32x16_bf16 v[50:65], v[86:89], v[82:85], v[50:65]
	ds_read_b64_tr_b16 v[86:87], v157 offset:32896
	ds_read_b64_tr_b16 v[88:89], v157 offset:35456
	s_waitcnt lgkmcnt(0)
	v_mfma_f32_32x32x16_bf16 v[34:49], v[86:89], v[82:85], v[34:49]
	ds_read_b64_tr_b16 v[86:87], v157 offset:32960
	ds_read_b64_tr_b16 v[88:89], v157 offset:35520
	s_waitcnt lgkmcnt(0)
	v_mfma_f32_32x32x16_bf16 v[18:33], v[86:89], v[82:85], v[18:33]
